# v18 + nt cache policy on the once-read residual-stream loads of the three EpiResid epilogues
# speedup vs baseline: 1.0032x; 1.0032x over previous
; __device__ __forceinline__ float bflo(unsigned u) { return __uint_as_float(u << 16); }
; __device__ __forceinline__ float bfhi(unsigned u) { return __uint_as_float(u & 0xffff0000u); }
; #define EPI_SCHED() do {} while (0)
; __device__ __forceinline__ f32x4 un_lo8(unsigned w) { return (f32x4){__builtin_amdgcn_cvt_f32_fp8((int)w, 0), __builtin_amdgcn_cvt_f32_fp8((int)w, 1), __builtin_amdgcn_cvt_f32_fp8((int)w, 2), __builtin_amdgcn_cvt_f32_fp8((int)w, 3)} * (1.f / 512.f); }
;     __device__ __forceinline__ void operator()(const AccT& acc, const Unit& u, int wr, int wc, int fr, int fq) const {
;         const int row0 = u.pm * 256 + wr * 64 + fr, col0 = u.pn * 256 + wc * 64 + 16 * fq;
;         const size_t off0 = (size_t)row0 * DM + col0;
;         u32x4 hr[4][2], lr[4];
; #pragma unroll
;         for (int i = 0; i < 4; ++i) { const size_t o = off0 + (size_t)(i * 16) * DM; hr[i][0] = *(const u32x4*)(XB + o); hr[i][1] = *(const u32x4*)(XB + o + 8); lr[i] = *(const u32x4*)(XL + o); }
;         EPI_SCHED();
; #pragma unroll
;         for (int idx = 0; idx < 8; ++idx) {
;             const int ai = idx >> 2, m = idx & 3, rofs = ai * 128 + m * 16;
;             const int row = row0 + rofs; float s = 0.f;
;             const size_t off = off0 + (size_t)rofs * DM;
;             const u32x4 h0 = hr[idx & 3][0], h1 = hr[idx & 3][1], l0 = lr[idx & 3];
;             if (idx + 4 < 8) { const size_t o = off0 + (size_t)(128 + (idx & 3) * 16) * DM;
;                 hr[idx & 3][0] = *(const u32x4*)(XB + o); hr[idx & 3][1] = *(const u32x4*)(XB + o + 8); lr[idx & 3] = *(const u32x4*)(XL + o); }
;             f32x4 x[4];
;             x[0] = (f32x4){bflo(h0.x), bfhi(h0.x), bflo(h0.y), bfhi(h0.y)} + un_lo8(l0.x);
;             x[1] = (f32x4){bflo(h0.z), bfhi(h0.z), bflo(h0.w), bfhi(h0.w)} + un_lo8(l0.y);
;             x[2] = (f32x4){bflo(h1.x), bfhi(h1.x), bflo(h1.y), bfhi(h1.y)} + un_lo8(l0.z);
;             x[3] = (f32x4){bflo(h1.z), bfhi(h1.z), bflo(h1.w), bfhi(h1.w)} + un_lo8(l0.w);
; #pragma unroll
;             for (int q = 0; q < 4; ++q) { x[q] = x[q] + scale * acc[ai][q >> 1][m][q & 1];
;                 s += (x[q][0] * x[q][0] + x[q][1] * x[q][1]) + (x[q][2] * x[q][2] + x[q][3] * x[q][3]); }
.LBB0_258:
	v_lshl_add_u32 v220, s45, 8, v239
	v_lshl_or_b32 v112, s43, 8, v243
	v_ashrrev_i32_e32 v221, 31, v220
	v_lshlrev_b64 v[114:115], 10, v[220:221]
	v_ashrrev_i32_e32 v113, 31, v112
	v_lshl_add_u64 v[112:113], v[114:115], 0, v[112:113]
	v_lshl_add_u64 v[214:215], v[112:113], 1, s[8:9]
	v_lshl_add_u64 v[208:209], s[12:13], 0, v[112:113]
	global_load_dwordx4 v[180:183], v[214:215], off offset:16 nt
	global_load_dwordx4 v[184:187], v[214:215], off nt
	global_load_dwordx4 v[176:179], v[208:209], off nt
	s_mov_b64 s[18:19], 0x8000
	v_add_co_u32_e32 v112, vcc, s85, v214
	v_lshl_add_u64 v[218:219], v[214:215], 0, s[18:19]
	s_nop 0
	v_addc_co_u32_e32 v113, vcc, 0, v215, vcc
	s_movk_i32 s18, 0x4000
	global_load_dwordx4 v[172:175], v[112:113], off nt
	global_load_dwordx4 v[164:167], v[218:219], off offset:16 nt
	v_add_co_u32_e32 v112, vcc, s18, v208
	v_lshl_add_u64 v[216:217], v[214:215], 0, s[56:57]
	s_nop 0
	v_addc_co_u32_e32 v113, vcc, 0, v209, vcc
	global_load_dwordx4 v[168:171], v[112:113], off nt
	v_add_co_u32_e32 v112, vcc, s84, v214
	s_mov_b64 s[18:19], 0x18000
	s_nop 0
	v_addc_co_u32_e32 v113, vcc, 0, v215, vcc
	global_load_dwordx4 v[160:163], v[112:113], off nt
	global_load_dwordx4 v[152:155], v[216:217], off offset:16 nt
	v_add_co_u32_e32 v112, vcc, s85, v208
	v_lshl_add_u64 v[212:213], v[214:215], 0, s[18:19]
	s_nop 0
	v_addc_co_u32_e32 v113, vcc, 0, v209, vcc
	global_load_dwordx4 v[156:159], v[112:113], off nt
	v_add_co_u32_e32 v112, vcc, s83, v214
	s_mov_b32 s18, 0xc000
	s_nop 0
	v_addc_co_u32_e32 v113, vcc, 0, v215, vcc
	global_load_dwordx4 v[140:143], v[112:113], off nt
	global_load_dwordx4 v[124:127], v[212:213], off offset:16 nt
	v_add_co_u32_e32 v112, vcc, s18, v208
	s_mov_b64 s[18:19], 0x40000
	s_nop 0
	v_addc_co_u32_e32 v113, vcc, 0, v209, vcc
	global_load_dwordx4 v[128:131], v[112:113], off nt
	v_add_co_u32_e32 v112, vcc, s82, v214
	v_lshl_add_u64 v[210:211], v[214:215], 0, s[18:19]
	s_nop 0
	v_addc_co_u32_e32 v113, vcc, 0, v215, vcc
	s_mov_b32 s18, 0x20000
	v_add_co_u32_e32 v120, vcc, s18, v208
	global_load_dwordx4 v[116:119], v[112:113], off nt
	s_nop 0
	global_load_dwordx4 v[112:115], v[210:211], off offset:16 nt
	v_addc_co_u32_e32 v121, vcc, 0, v209, vcc
	global_load_dwordx4 v[120:123], v[120:121], off nt
	s_waitcnt vmcnt(0)
	v_lshlrev_b32_e32 v222, 16, v184
	v_cvt_f32_fp8_sdwa v230, v176 src0_sel:BYTE_2
	v_cvt_f32_fp8_sdwa v231, v176 src0_sel:BYTE_3
	v_and_b32_e32 v223, 0xffff0000, v184
	v_lshlrev_b32_e32 v184, 16, v185
	v_and_b32_e32 v185, 0xffff0000, v185
	v_cvt_f32_fp8_e32 v228, v176
	v_cvt_f32_fp8_sdwa v229, v176 src0_sel:BYTE_1
	v_pk_fma_f32 v[184:185], v[230:231], s[76:77], v[184:185] op_sel_hi:[1,0,1]
	v_cvt_f32_fp8_e32 v230, v177
	v_cvt_f32_fp8_sdwa v231, v177 src0_sel:BYTE_1
	v_cvt_f32_fp8_sdwa v176, v177 src0_sel:BYTE_2
	v_cvt_f32_fp8_sdwa v177, v177 src0_sel:BYTE_3
	v_cvt_f32_fp8_sdwa v232, v178 src0_sel:BYTE_2
	v_cvt_f32_fp8_sdwa v233, v178 src0_sel:BYTE_3
	v_pk_fma_f32 v[222:223], v[228:229], s[76:77], v[222:223] op_sel_hi:[1,0,1]
	v_lshlrev_b32_e32 v228, 16, v186
	v_and_b32_e32 v229, 0xffff0000, v186
	v_lshlrev_b32_e32 v186, 16, v187
	v_and_b32_e32 v187, 0xffff0000, v187
	v_pk_fma_f32 v[176:177], v[176:177], s[76:77], v[186:187] op_sel_hi:[1,0,1]
	v_pk_fma_f32 v[186:187], v[230:231], s[76:77], v[228:229] op_sel_hi:[1,0,1]
	v_lshlrev_b32_e32 v228, 16, v180
	v_and_b32_e32 v229, 0xffff0000, v180
	v_lshlrev_b32_e32 v180, 16, v181
	v_and_b32_e32 v181, 0xffff0000, v181
	v_cvt_f32_fp8_e32 v230, v178
	v_cvt_f32_fp8_sdwa v231, v178 src0_sel:BYTE_1
	v_pk_fma_f32 v[180:181], v[232:233], s[76:77], v[180:181] op_sel_hi:[1,0,1]
	v_cvt_f32_fp8_e32 v232, v179
	v_cvt_f32_fp8_sdwa v233, v179 src0_sel:BYTE_1
	v_cvt_f32_fp8_sdwa v178, v179 src0_sel:BYTE_2
	v_cvt_f32_fp8_sdwa v179, v179 src0_sel:BYTE_3
	v_pk_fma_f32 v[228:229], v[230:231], s[76:77], v[228:229] op_sel_hi:[1,0,1]
	v_lshlrev_b32_e32 v230, 16, v182
	v_and_b32_e32 v231, 0xffff0000, v182
	v_lshlrev_b32_e32 v182, 16, v183
	v_and_b32_e32 v183, 0xffff0000, v183
	v_pk_fma_f32 v[178:179], v[178:179], s[76:77], v[182:183] op_sel_hi:[1,0,1]
	v_pk_fma_f32 v[182:183], v[232:233], s[76:77], v[230:231] op_sel_hi:[1,0,1]
	v_pk_fma_f32 v[148:149], v[148:149], 0.5, v[222:223] op_sel_hi:[1,0,1]
	v_pk_fma_f32 v[150:151], v[150:151], 0.5, v[184:185] op_sel_hi:[1,0,1]
	v_pk_fma_f32 v[182:183], v[132:133], 0.5, v[182:183] op_sel_hi:[1,0,1]
	v_mul_f32_e32 v132, v149, v149
	v_mul_f32_e32 v133, v151, v151
	v_pk_fma_f32 v[184:185], v[144:145], 0.5, v[186:187] op_sel_hi:[1,0,1]
	v_pk_fma_f32 v[146:147], v[146:147], 0.5, v[176:177] op_sel_hi:[1,0,1]
	v_fmac_f32_e32 v132, v148, v148
	v_fmac_f32_e32 v133, v150, v150
	v_pk_fma_f32 v[178:179], v[134:135], 0.5, v[178:179] op_sel_hi:[1,0,1]
	v_add_f32_e32 v132, v132, v133
	v_mul_f32_e32 v133, v185, v185
	v_mul_f32_e32 v134, v147, v147
	v_fmac_f32_e32 v133, v184, v184
	v_fmac_f32_e32 v134, v146, v146
	v_pk_fma_f32 v[176:177], v[136:137], 0.5, v[228:229] op_sel_hi:[1,0,1]
	v_pk_fma_f32 v[180:181], v[138:139], 0.5, v[180:181] op_sel_hi:[1,0,1]
	v_add_f32_e32 v133, v133, v134
	v_add_f32_e32 v132, v132, v133
	v_mul_f32_e32 v133, v177, v177
	v_mul_f32_e32 v134, v181, v181
	v_fmac_f32_e32 v133, v176, v176
	v_fmac_f32_e32 v134, v180, v180
	v_add_f32_e32 v133, v133, v134
	v_add_f32_e32 v132, v132, v133
	v_mul_f32_e32 v133, v183, v183
	v_mul_f32_e32 v134, v179, v179
	v_fmac_f32_e32 v133, v182, v182
	v_fmac_f32_e32 v134, v178, v178
	v_add_f32_e32 v133, v133, v134
	v_add_f32_e32 v186, v132, v133
	v_cvt_pk_bf16_f32 v132, v148, v149
	v_cvt_pk_bf16_f32 v133, v150, v151
	v_lshlrev_b32_e32 v144, 16, v132
	v_and_b32_e32 v145, 0xffff0000, v132
; __device__ __forceinline__ float bflo(unsigned u) { return __uint_as_float(u << 16); }
; __device__ __forceinline__ float bfhi(unsigned u) { return __uint_as_float(u & 0xffff0000u); }
;     __device__ __forceinline__ void operator()(const AccT& acc, const Unit& u, int wr, int wc, int fr, int fq) const {
;     ...
;             if (idx + 4 < 8) { const size_t o = off0 + (size_t)(128 + (idx & 3) * 16) * DM;
;                 hr[idx & 3][0] = *(const u32x4*)(XB + o); hr[idx & 3][1] = *(const u32x4*)(XB + o + 8); lr[idx & 3] = *(const u32x4*)(XL + o); }
;             f32x4 x[4];
;             x[0] = (f32x4){bflo(h0.x), bfhi(h0.x), bflo(h0.y), bfhi(h0.y)} + un_lo8(l0.x);
;             x[1] = (f32x4){bflo(h0.z), bfhi(h0.z), bflo(h0.w), bfhi(h0.w)} + un_lo8(l0.y);
;             x[2] = (f32x4){bflo(h1.x), bfhi(h1.x), bflo(h1.y), bfhi(h1.y)} + un_lo8(l0.z);
;             x[3] = (f32x4){bflo(h1.z), bfhi(h1.z), bflo(h1.w), bfhi(h1.w)} + un_lo8(l0.w);
; #pragma unroll
;             for (int q = 0; q < 4; ++q) { x[q] = x[q] + scale * acc[ai][q >> 1][m][q & 1];
;                 s += (x[q][0] * x[q][0] + x[q][1] * x[q][1]) + (x[q][2] * x[q][2] + x[q][3] * x[q][3]); }
;             if (last) { float* p = OUT + off;
; #pragma unroll
;                 for (int q = 0; q < 4; ++q) *(f32x4*)(p + 4 * q) = x[q];
;             } else {
;                 u32x4 w0, w1, v0;
;                 w0.x = pk2(x[0][0], x[0][1]); w0.y = pk2(x[0][2], x[0][3]); w0.z = pk2(x[1][0], x[1][1]); w0.w = pk2(x[1][2], x[1][3]);
;                 w1.x = pk2(x[2][0], x[2][1]); w1.y = pk2(x[2][2], x[2][3]); w1.z = pk2(x[3][0], x[3][1]); w1.w = pk2(x[3][2], x[3][3]);
;                 v0.x = pk_lo8(x[0][0] - bflo(w0.x), x[0][1] - bfhi(w0.x), x[0][2] - bflo(w0.y), x[0][3] - bfhi(w0.y));
;                 v0.y = pk_lo8(x[1][0] - bflo(w0.z), x[1][1] - bfhi(w0.z), x[1][2] - bflo(w0.w), x[1][3] - bfhi(w0.w));
;                 v0.z = pk_lo8(x[2][0] - bflo(w1.x), x[2][1] - bfhi(w1.x), x[2][2] - bflo(w1.y), x[2][3] - bfhi(w1.y));
;                 v0.w = pk_lo8(x[3][0] - bflo(w1.z), x[3][1] - bfhi(w1.z), x[3][2] - bflo(w1.w), x[3][3] - bfhi(w1.w));
;                 u32x4* xb = (u32x4*)(XB + off); xb[0] = w0; xb[1] = w1;
;                 *(u32x4*)(XL + off) = v0;
;                 s += shx(s, LANE_, 16); s += shx(s, LANE_, 32);
;                 if (fq == 0) atomicAdd(ssq_next + row, s);
	v_sub_f32_e32 v144, v148, v144
	v_sub_f32_e32 v145, v149, v145
	v_lshlrev_b32_e32 v148, 16, v133
	v_sub_f32_e32 v148, v150, v148
	v_mul_f32_e32 v150, 0x44000000, v144
	v_mul_f32_e32 v145, 0x44000000, v145
	v_mov_b32_e32 v144, v189
	v_cvt_pk_fp8_f32 v144, v150, v145
	v_and_b32_e32 v149, 0xffff0000, v133
	v_sub_f32_e32 v149, v151, v149
	v_cvt_pk_bf16_f32 v134, v184, v185
	v_cvt_pk_bf16_f32 v135, v146, v147
	v_mul_f32_e32 v145, 0x44000000, v148
	v_mul_f32_e32 v148, 0x44000000, v149
	v_cvt_pk_fp8_f32 v144, v145, v148 op_sel:[0,0,1]
	v_lshlrev_b32_e32 v145, 16, v134
	v_and_b32_e32 v148, 0xffff0000, v134
	v_lshlrev_b32_e32 v149, 16, v135
	v_sub_f32_e32 v145, v184, v145
	v_sub_f32_e32 v148, v185, v148
	v_sub_f32_e32 v146, v146, v149
	v_and_b32_e32 v149, 0xffff0000, v135
	v_sub_f32_e32 v147, v147, v149
	v_mul_f32_e32 v149, 0x44000000, v145
	v_mul_f32_e32 v148, 0x44000000, v148
	v_mov_b32_e32 v145, v189
	v_cvt_pk_fp8_f32 v145, v149, v148
	v_cvt_pk_bf16_f32 v136, v176, v177
	v_mul_f32_e32 v146, 0x44000000, v146
	v_mul_f32_e32 v147, 0x44000000, v147
	v_cvt_pk_fp8_f32 v145, v146, v147 op_sel:[0,0,1]
	v_lshlrev_b32_e32 v146, 16, v136
	v_and_b32_e32 v147, 0xffff0000, v136
	v_sub_f32_e32 v146, v176, v146
	v_sub_f32_e32 v147, v177, v147
	v_mul_f32_e32 v150, 0x44000000, v146
	v_mul_f32_e32 v147, 0x44000000, v147
	v_mov_b32_e32 v146, v189
	v_cvt_pk_bf16_f32 v137, v180, v181
	v_cvt_pk_fp8_f32 v146, v150, v147
	v_lshlrev_b32_e32 v148, 16, v137
	v_and_b32_e32 v149, 0xffff0000, v137
	v_sub_f32_e32 v148, v180, v148
	v_sub_f32_e32 v149, v181, v149
	v_cvt_pk_bf16_f32 v138, v182, v183
	v_mul_f32_e32 v147, 0x44000000, v148
	v_mul_f32_e32 v148, 0x44000000, v149
	v_cvt_pk_fp8_f32 v146, v147, v148 op_sel:[0,0,1]
	v_lshlrev_b32_e32 v147, 16, v138
	v_and_b32_e32 v148, 0xffff0000, v138
	v_sub_f32_e32 v147, v182, v147
	v_sub_f32_e32 v148, v183, v148
	v_mul_f32_e32 v151, 0x44000000, v147
	v_mul_f32_e32 v148, 0x44000000, v148
	v_mov_b32_e32 v147, v189
	v_cvt_pk_bf16_f32 v139, v178, v179
	v_cvt_pk_fp8_f32 v147, v151, v148
	v_lshlrev_b32_e32 v149, 16, v139
	v_and_b32_e32 v150, 0xffff0000, v139
	v_sub_f32_e32 v149, v178, v149
	v_sub_f32_e32 v150, v179, v150
	v_mul_f32_e32 v148, 0x44000000, v149
	v_mul_f32_e32 v149, 0x44000000, v150
	v_cvt_pk_fp8_f32 v147, v148, v149 op_sel:[0,0,1]
	global_store_dwordx4 v[214:215], v[132:135], off
	global_store_dwordx4 v[214:215], v[136:139], off offset:16
	global_store_dwordx4 v[208:209], v[144:147], off
	ds_bpermute_b32 v132, v241, v186
	v_lshl_add_u64 v[148:149], v[220:221], 2, s[10:11]
	s_waitcnt lgkmcnt(0)
	v_add_f32_e32 v132, v186, v132
	ds_bpermute_b32 v133, v242, v132
	s_and_saveexec_b64 s[18:19], s[0:1]
	s_cbranch_execz .LBB0_260
	s_waitcnt lgkmcnt(0)
	v_add_f32_e32 v132, v132, v133
	global_atomic_add_f32 v[148:149], v132, off
.LBB0_260:
	s_or_b64 exec, exec, s[18:19]
	v_add_co_u32_e32 v132, vcc, 0x48000, v214
	s_mov_b64 s[18:19], 0x48000
	s_waitcnt lgkmcnt(0)
	v_addc_co_u32_e32 v133, vcc, 0, v215, vcc
	v_add_co_u32_e32 v136, vcc, 0x24000, v208
	v_lshl_add_u64 v[150:151], v[214:215], 0, s[18:19]
	s_nop 0
	v_addc_co_u32_e32 v137, vcc, 0, v209, vcc
	global_load_dwordx4 v[144:147], v[132:133], off nt
	s_nop 0
	global_load_dwordx4 v[132:135], v[150:151], off offset:16 nt
	v_cvt_f32_fp8_sdwa v180, v168 src0_sel:BYTE_2
	global_load_dwordx4 v[136:139], v[136:137], off nt
	v_cvt_f32_fp8_sdwa v181, v168 src0_sel:BYTE_3
	v_lshlrev_b32_e32 v176, 16, v172
	v_and_b32_e32 v177, 0xffff0000, v172
	v_cvt_f32_fp8_e32 v178, v168
	v_cvt_f32_fp8_sdwa v179, v168 src0_sel:BYTE_1
	v_lshlrev_b32_e32 v172, 16, v173
	v_and_b32_e32 v173, 0xffff0000, v173
	v_pk_fma_f32 v[172:173], v[180:181], s[76:77], v[172:173] op_sel_hi:[1,0,1]
	v_cvt_f32_fp8_e32 v168, v169
	v_cvt_f32_fp8_sdwa v180, v169 src0_sel:BYTE_2
	v_cvt_f32_fp8_sdwa v181, v169 src0_sel:BYTE_3
	v_cvt_f32_fp8_sdwa v169, v169 src0_sel:BYTE_1
	v_cvt_f32_fp8_sdwa v182, v170 src0_sel:BYTE_2
	v_cvt_f32_fp8_sdwa v183, v170 src0_sel:BYTE_3
	v_pk_fma_f32 v[176:177], v[178:179], s[76:77], v[176:177] op_sel_hi:[1,0,1]
	v_lshlrev_b32_e32 v178, 16, v174
	v_and_b32_e32 v179, 0xffff0000, v174
	v_lshlrev_b32_e32 v174, 16, v175
	v_and_b32_e32 v175, 0xffff0000, v175
	v_pk_fma_f32 v[174:175], v[180:181], s[76:77], v[174:175] op_sel_hi:[1,0,1]
	v_pk_fma_f32 v[168:169], v[168:169], s[76:77], v[178:179] op_sel_hi:[1,0,1]
	v_lshlrev_b32_e32 v178, 16, v164
	v_and_b32_e32 v179, 0xffff0000, v164
	v_cvt_f32_fp8_e32 v180, v170
	v_cvt_f32_fp8_sdwa v181, v170 src0_sel:BYTE_1
	v_lshlrev_b32_e32 v164, 16, v165
	v_and_b32_e32 v165, 0xffff0000, v165
	v_pk_fma_f32 v[164:165], v[182:183], s[76:77], v[164:165] op_sel_hi:[1,0,1]
	v_cvt_f32_fp8_sdwa v182, v171 src0_sel:BYTE_2
	v_cvt_f32_fp8_sdwa v183, v171 src0_sel:BYTE_3
	v_pk_fma_f32 v[178:179], v[180:181], s[76:77], v[178:179] op_sel_hi:[1,0,1]
	v_lshlrev_b32_e32 v180, 16, v166
	v_and_b32_e32 v181, 0xffff0000, v166
	v_lshlrev_b32_e32 v166, 16, v167
	v_and_b32_e32 v167, 0xffff0000, v167
	v_pk_fma_f32 v[166:167], v[182:183], s[76:77], v[166:167] op_sel_hi:[1,0,1]
	v_pk_fma_f32 v[108:109], v[108:109], 0.5, v[176:177] op_sel_hi:[1,0,1]
	v_pk_fma_f32 v[110:111], v[110:111], 0.5, v[172:173] op_sel_hi:[1,0,1]
	v_pk_fma_f32 v[166:167], v[98:99], 0.5, v[166:167] op_sel_hi:[1,0,1]
	v_mul_f32_e32 v98, v109, v109
	v_mul_f32_e32 v99, v111, v111
	v_pk_fma_f32 v[168:169], v[104:105], 0.5, v[168:169] op_sel_hi:[1,0,1]
	v_pk_fma_f32 v[172:173], v[106:107], 0.5, v[174:175] op_sel_hi:[1,0,1]
	v_fmac_f32_e32 v98, v108, v108
	v_fmac_f32_e32 v99, v110, v110
	v_cvt_f32_fp8_e32 v170, v171
	v_cvt_f32_fp8_sdwa v171, v171 src0_sel:BYTE_1
	v_pk_fma_f32 v[174:175], v[100:101], 0.5, v[178:179] op_sel_hi:[1,0,1]
; __device__ __forceinline__ float bflo(unsigned u) { return __uint_as_float(u << 16); }
; __device__ __forceinline__ float bfhi(unsigned u) { return __uint_as_float(u & 0xffff0000u); }
;     __device__ __forceinline__ void operator()(const AccT& acc, const Unit& u, int wr, int wc, int fr, int fq) const {
;     ...
;             if (idx + 4 < 8) { const size_t o = off0 + (size_t)(128 + (idx & 3) * 16) * DM;
;                 hr[idx & 3][0] = *(const u32x4*)(XB + o); hr[idx & 3][1] = *(const u32x4*)(XB + o + 8); lr[idx & 3] = *(const u32x4*)(XL + o); }
;             f32x4 x[4];
;             x[0] = (f32x4){bflo(h0.x), bfhi(h0.x), bflo(h0.y), bfhi(h0.y)} + un_lo8(l0.x);
;             x[1] = (f32x4){bflo(h0.z), bfhi(h0.z), bflo(h0.w), bfhi(h0.w)} + un_lo8(l0.y);
;             x[2] = (f32x4){bflo(h1.x), bfhi(h1.x), bflo(h1.y), bfhi(h1.y)} + un_lo8(l0.z);
;             x[3] = (f32x4){bflo(h1.z), bfhi(h1.z), bflo(h1.w), bfhi(h1.w)} + un_lo8(l0.w);
; #pragma unroll
;             for (int q = 0; q < 4; ++q) { x[q] = x[q] + scale * acc[ai][q >> 1][m][q & 1];
;                 s += (x[q][0] * x[q][0] + x[q][1] * x[q][1]) + (x[q][2] * x[q][2] + x[q][3] * x[q][3]); }
;             if (last) { float* p = OUT + off;
; #pragma unroll
;                 for (int q = 0; q < 4; ++q) *(f32x4*)(p + 4 * q) = x[q];
;             } else {
;                 u32x4 w0, w1, v0;
;                 w0.x = pk2(x[0][0], x[0][1]); w0.y = pk2(x[0][2], x[0][3]); w0.z = pk2(x[1][0], x[1][1]); w0.w = pk2(x[1][2], x[1][3]);
;                 w1.x = pk2(x[2][0], x[2][1]); w1.y = pk2(x[2][2], x[2][3]); w1.z = pk2(x[3][0], x[3][1]); w1.w = pk2(x[3][2], x[3][3]);
;                 v0.x = pk_lo8(x[0][0] - bflo(w0.x), x[0][1] - bfhi(w0.x), x[0][2] - bflo(w0.y), x[0][3] - bfhi(w0.y));
;                 v0.y = pk_lo8(x[1][0] - bflo(w0.z), x[1][1] - bfhi(w0.z), x[1][2] - bflo(w0.w), x[1][3] - bfhi(w0.w));
;                 v0.z = pk_lo8(x[2][0] - bflo(w1.x), x[2][1] - bfhi(w1.x), x[2][2] - bflo(w1.y), x[2][3] - bfhi(w1.y));
;                 v0.w = pk_lo8(x[3][0] - bflo(w1.z), x[3][1] - bfhi(w1.z), x[3][2] - bflo(w1.w), x[3][3] - bfhi(w1.w));
;                 u32x4* xb = (u32x4*)(XB + off); xb[0] = w0; xb[1] = w1;
;                 *(u32x4*)(XL + off) = v0;
;                 s += shx(s, LANE_, 16); s += shx(s, LANE_, 32);
;                 if (fq == 0) atomicAdd(ssq_next + row, s);
	v_add_f32_e32 v98, v98, v99
	v_mul_f32_e32 v99, v169, v169
	v_mul_f32_e32 v100, v173, v173
	v_fmac_f32_e32 v99, v168, v168
	v_fmac_f32_e32 v100, v172, v172
	v_pk_fma_f32 v[164:165], v[102:103], 0.5, v[164:165] op_sel_hi:[1,0,1]
	v_add_f32_e32 v99, v99, v100
	v_add_f32_e32 v98, v98, v99
	v_mul_f32_e32 v99, v175, v175
	v_mul_f32_e32 v100, v165, v165
	v_pk_fma_f32 v[170:171], v[170:171], s[76:77], v[180:181] op_sel_hi:[1,0,1]
	v_fmac_f32_e32 v99, v174, v174
	v_fmac_f32_e32 v100, v164, v164
	v_pk_fma_f32 v[96:97], v[96:97], 0.5, v[170:171] op_sel_hi:[1,0,1]
	v_add_f32_e32 v99, v99, v100
	v_add_f32_e32 v98, v98, v99
	v_mul_f32_e32 v99, v97, v97
	v_mul_f32_e32 v100, v167, v167
	v_fmac_f32_e32 v99, v96, v96
	v_fmac_f32_e32 v100, v166, v166
	v_add_f32_e32 v99, v99, v100
	v_add_f32_e32 v170, v98, v99
	v_cvt_pk_bf16_f32 v98, v108, v109
	v_cvt_pk_bf16_f32 v99, v110, v111
	v_lshlrev_b32_e32 v106, 16, v98
	v_and_b32_e32 v107, 0xffff0000, v98
	v_sub_f32_e32 v106, v108, v106
	v_sub_f32_e32 v107, v109, v107
	v_lshlrev_b32_e32 v108, 16, v99
	v_sub_f32_e32 v108, v110, v108
	v_mul_f32_e32 v110, 0x44000000, v106
	v_mul_f32_e32 v107, 0x44000000, v107
	v_mov_b32_e32 v106, v189
	v_cvt_pk_fp8_f32 v106, v110, v107
	v_and_b32_e32 v109, 0xffff0000, v99
	v_sub_f32_e32 v107, v111, v109
	v_cvt_pk_bf16_f32 v100, v168, v169
	v_mul_f32_e32 v108, 0x44000000, v108
	v_mul_f32_e32 v107, 0x44000000, v107
	v_cvt_pk_fp8_f32 v106, v108, v107 op_sel:[0,0,1]
	v_lshlrev_b32_e32 v107, 16, v100
	v_and_b32_e32 v108, 0xffff0000, v100
	v_sub_f32_e32 v107, v168, v107
	v_sub_f32_e32 v108, v169, v108
	v_mul_f32_e32 v111, 0x44000000, v107
	v_mul_f32_e32 v108, 0x44000000, v108
	v_mov_b32_e32 v107, v189
	v_cvt_pk_bf16_f32 v101, v172, v173
	v_cvt_pk_fp8_f32 v107, v111, v108
	v_lshlrev_b32_e32 v109, 16, v101
	v_and_b32_e32 v110, 0xffff0000, v101
	v_sub_f32_e32 v109, v172, v109
	v_sub_f32_e32 v108, v173, v110
	v_cvt_pk_bf16_f32 v102, v174, v175
	v_mul_f32_e32 v109, 0x44000000, v109
	v_mul_f32_e32 v108, 0x44000000, v108
	v_cvt_pk_bf16_f32 v103, v164, v165
	v_cvt_pk_fp8_f32 v107, v109, v108 op_sel:[0,0,1]
	v_lshlrev_b32_e32 v108, 16, v102
	v_and_b32_e32 v109, 0xffff0000, v102
	v_sub_f32_e32 v108, v174, v108
	v_sub_f32_e32 v109, v175, v109
	v_lshlrev_b32_e32 v110, 16, v103
	v_sub_f32_e32 v110, v164, v110
	v_mul_f32_e32 v164, 0x44000000, v108
	v_mul_f32_e32 v109, 0x44000000, v109
	v_mov_b32_e32 v108, v189
	v_cvt_pk_fp8_f32 v108, v164, v109
	v_and_b32_e32 v111, 0xffff0000, v103
	v_sub_f32_e32 v109, v165, v111
	v_cvt_pk_bf16_f32 v104, v96, v97
	v_mul_f32_e32 v110, 0x44000000, v110
	v_mul_f32_e32 v109, 0x44000000, v109
	v_cvt_pk_fp8_f32 v108, v110, v109 op_sel:[0,0,1]
	v_lshlrev_b32_e32 v109, 16, v104
	v_cvt_pk_bf16_f32 v105, v166, v167
	v_sub_f32_e32 v96, v96, v109
	v_and_b32_e32 v109, 0xffff0000, v104
	v_sub_f32_e32 v97, v97, v109
	v_lshlrev_b32_e32 v109, 16, v105
	v_sub_f32_e32 v110, v166, v109
	v_mul_f32_e32 v96, 0x44000000, v96
	v_mul_f32_e32 v97, 0x44000000, v97
	v_mov_b32_e32 v109, v189
	v_cvt_pk_fp8_f32 v109, v96, v97
	ds_bpermute_b32 v96, v241, v170
	v_and_b32_e32 v111, 0xffff0000, v105
	v_sub_f32_e32 v97, v167, v111
	v_mul_f32_e32 v110, 0x44000000, v110
	v_mul_f32_e32 v97, 0x44000000, v97
	s_waitcnt lgkmcnt(0)
	v_add_f32_e32 v96, v170, v96
	v_cvt_pk_fp8_f32 v109, v110, v97 op_sel:[0,0,1]
	ds_bpermute_b32 v97, v242, v96
	s_mov_b64 s[18:19], 0x4000
	v_lshl_add_u64 v[110:111], v[208:209], 0, s[18:19]
	global_store_dwordx4 v[218:219], v[98:101], off
	global_store_dwordx4 v[218:219], v[102:105], off offset:16
	global_store_dwordx4 v[110:111], v[106:109], off
	s_and_saveexec_b64 s[18:19], s[0:1]
	s_cbranch_execz .LBB0_262
	s_waitcnt lgkmcnt(0)
	v_add_f32_e32 v96, v96, v97
	global_atomic_add_f32 v[148:149], v96, off offset:64
.LBB0_262:
	s_or_b64 exec, exec, s[18:19]
	v_add_co_u32_e32 v96, vcc, 0x50000, v214
	s_mov_b64 s[18:19], 0x50000
	s_waitcnt lgkmcnt(0)
	v_addc_co_u32_e32 v97, vcc, 0, v215, vcc
	v_add_co_u32_e32 v100, vcc, 0x28000, v208
	v_lshl_add_u64 v[108:109], v[214:215], 0, s[18:19]
	s_nop 0
	v_addc_co_u32_e32 v101, vcc, 0, v209, vcc
	global_load_dwordx4 v[104:107], v[96:97], off nt
	s_nop 0
	global_load_dwordx4 v[96:99], v[108:109], off offset:16 nt
	v_cvt_f32_fp8_sdwa v166, v156 src0_sel:BYTE_2
	global_load_dwordx4 v[100:103], v[100:101], off nt
	v_cvt_f32_fp8_sdwa v167, v156 src0_sel:BYTE_3
	v_lshlrev_b32_e32 v110, 16, v160
	v_and_b32_e32 v111, 0xffff0000, v160
	v_cvt_f32_fp8_e32 v164, v156
	v_cvt_f32_fp8_sdwa v165, v156 src0_sel:BYTE_1
	v_lshlrev_b32_e32 v160, 16, v161
	v_and_b32_e32 v161, 0xffff0000, v161
	v_pk_fma_f32 v[160:161], v[166:167], s[76:77], v[160:161] op_sel_hi:[1,0,1]
	v_cvt_f32_fp8_e32 v156, v157
	v_cvt_f32_fp8_sdwa v166, v157 src0_sel:BYTE_2
	v_cvt_f32_fp8_sdwa v167, v157 src0_sel:BYTE_3
	v_cvt_f32_fp8_sdwa v157, v157 src0_sel:BYTE_1
	v_cvt_f32_fp8_sdwa v168, v158 src0_sel:BYTE_2
	v_cvt_f32_fp8_sdwa v169, v158 src0_sel:BYTE_3
	v_pk_fma_f32 v[110:111], v[164:165], s[76:77], v[110:111] op_sel_hi:[1,0,1]
	v_lshlrev_b32_e32 v164, 16, v162
	v_and_b32_e32 v165, 0xffff0000, v162
	v_lshlrev_b32_e32 v162, 16, v163
	v_and_b32_e32 v163, 0xffff0000, v163
	v_pk_fma_f32 v[162:163], v[166:167], s[76:77], v[162:163] op_sel_hi:[1,0,1]
	v_pk_fma_f32 v[156:157], v[156:157], s[76:77], v[164:165] op_sel_hi:[1,0,1]
	v_lshlrev_b32_e32 v164, 16, v152
	v_and_b32_e32 v165, 0xffff0000, v152
	v_cvt_f32_fp8_e32 v166, v158
	v_cvt_f32_fp8_sdwa v167, v158 src0_sel:BYTE_1
	v_lshlrev_b32_e32 v152, 16, v153
	v_and_b32_e32 v153, 0xffff0000, v153
	v_pk_fma_f32 v[152:153], v[168:169], s[76:77], v[152:153] op_sel_hi:[1,0,1]
	v_cvt_f32_fp8_sdwa v168, v159 src0_sel:BYTE_2
	v_cvt_f32_fp8_sdwa v169, v159 src0_sel:BYTE_3
; __device__ __forceinline__ float bflo(unsigned u) { return __uint_as_float(u << 16); }
; __device__ __forceinline__ float bfhi(unsigned u) { return __uint_as_float(u & 0xffff0000u); }
; __device__ __forceinline__ unsigned pk2(float lo, float hi) { f32x2 v = {lo, hi}; bf2_t b = __builtin_convertvector(v, bf2_t); return __builtin_bit_cast(unsigned, b); }
;     __device__ __forceinline__ void operator()(const AccT& acc, const Unit& u, int wr, int wc, int fr, int fq) const {
;     ...
;             x[0] = (f32x4){bflo(h0.x), bfhi(h0.x), bflo(h0.y), bfhi(h0.y)} + un_lo8(l0.x);
;             x[1] = (f32x4){bflo(h0.z), bfhi(h0.z), bflo(h0.w), bfhi(h0.w)} + un_lo8(l0.y);
;             x[2] = (f32x4){bflo(h1.x), bfhi(h1.x), bflo(h1.y), bfhi(h1.y)} + un_lo8(l0.z);
;             x[3] = (f32x4){bflo(h1.z), bfhi(h1.z), bflo(h1.w), bfhi(h1.w)} + un_lo8(l0.w);
; #pragma unroll
;             for (int q = 0; q < 4; ++q) { x[q] = x[q] + scale * acc[ai][q >> 1][m][q & 1];
;                 s += (x[q][0] * x[q][0] + x[q][1] * x[q][1]) + (x[q][2] * x[q][2] + x[q][3] * x[q][3]); }
;             if (last) { float* p = OUT + off;
; #pragma unroll
;                 for (int q = 0; q < 4; ++q) *(f32x4*)(p + 4 * q) = x[q];
;             } else {
;                 u32x4 w0, w1, v0;
;                 w0.x = pk2(x[0][0], x[0][1]); w0.y = pk2(x[0][2], x[0][3]); w0.z = pk2(x[1][0], x[1][1]); w0.w = pk2(x[1][2], x[1][3]);
;                 w1.x = pk2(x[2][0], x[2][1]); w1.y = pk2(x[2][2], x[2][3]); w1.z = pk2(x[3][0], x[3][1]); w1.w = pk2(x[3][2], x[3][3]);
;                 v0.x = pk_lo8(x[0][0] - bflo(w0.x), x[0][1] - bfhi(w0.x), x[0][2] - bflo(w0.y), x[0][3] - bfhi(w0.y));
;                 v0.y = pk_lo8(x[1][0] - bflo(w0.z), x[1][1] - bfhi(w0.z), x[1][2] - bflo(w0.w), x[1][3] - bfhi(w0.w));
;                 v0.z = pk_lo8(x[2][0] - bflo(w1.x), x[2][1] - bfhi(w1.x), x[2][2] - bflo(w1.y), x[2][3] - bfhi(w1.y));
;                 v0.w = pk_lo8(x[3][0] - bflo(w1.z), x[3][1] - bfhi(w1.z), x[3][2] - bflo(w1.w), x[3][3] - bfhi(w1.w));
;                 u32x4* xb = (u32x4*)(XB + off); xb[0] = w0; xb[1] = w1;
;                 *(u32x4*)(XL + off) = v0;
;                 s += shx(s, LANE_, 16); s += shx(s, LANE_, 32);
;                 if (fq == 0) atomicAdd(ssq_next + row, s);
	v_pk_fma_f32 v[164:165], v[166:167], s[76:77], v[164:165] op_sel_hi:[1,0,1]
	v_lshlrev_b32_e32 v166, 16, v154
	v_and_b32_e32 v167, 0xffff0000, v154
	v_lshlrev_b32_e32 v154, 16, v155
	v_and_b32_e32 v155, 0xffff0000, v155
	v_pk_fma_f32 v[154:155], v[168:169], s[76:77], v[154:155] op_sel_hi:[1,0,1]
	v_pk_fma_f32 v[92:93], v[92:93], 0.5, v[110:111] op_sel_hi:[1,0,1]
	v_pk_fma_f32 v[94:95], v[94:95], 0.5, v[160:161] op_sel_hi:[1,0,1]
	v_pk_fma_f32 v[154:155], v[82:83], 0.5, v[154:155] op_sel_hi:[1,0,1]
	v_mul_f32_e32 v82, v93, v93
	v_mul_f32_e32 v83, v95, v95
	v_pk_fma_f32 v[110:111], v[88:89], 0.5, v[156:157] op_sel_hi:[1,0,1]
	v_pk_fma_f32 v[156:157], v[90:91], 0.5, v[162:163] op_sel_hi:[1,0,1]
	v_fmac_f32_e32 v82, v92, v92
	v_fmac_f32_e32 v83, v94, v94
	v_cvt_f32_fp8_e32 v158, v159
	v_cvt_f32_fp8_sdwa v159, v159 src0_sel:BYTE_1
	v_pk_fma_f32 v[160:161], v[84:85], 0.5, v[164:165] op_sel_hi:[1,0,1]
	v_add_f32_e32 v82, v82, v83
	v_mul_f32_e32 v83, v111, v111
	v_mul_f32_e32 v84, v157, v157
	v_fmac_f32_e32 v83, v110, v110
	v_fmac_f32_e32 v84, v156, v156
	v_pk_fma_f32 v[152:153], v[86:87], 0.5, v[152:153] op_sel_hi:[1,0,1]
	v_add_f32_e32 v83, v83, v84
	v_add_f32_e32 v82, v82, v83
	v_mul_f32_e32 v83, v161, v161
	v_mul_f32_e32 v84, v153, v153
	v_pk_fma_f32 v[158:159], v[158:159], s[76:77], v[166:167] op_sel_hi:[1,0,1]
	v_fmac_f32_e32 v83, v160, v160
	v_fmac_f32_e32 v84, v152, v152
	v_pk_fma_f32 v[80:81], v[80:81], 0.5, v[158:159] op_sel_hi:[1,0,1]
	v_add_f32_e32 v83, v83, v84
	v_add_f32_e32 v82, v82, v83
	v_mul_f32_e32 v83, v81, v81
	v_mul_f32_e32 v84, v155, v155
	v_fmac_f32_e32 v83, v80, v80
	v_fmac_f32_e32 v84, v154, v154
	v_add_f32_e32 v83, v83, v84
	v_add_f32_e32 v158, v82, v83
	v_cvt_pk_bf16_f32 v82, v92, v93
	v_cvt_pk_bf16_f32 v83, v94, v95
	v_lshlrev_b32_e32 v90, 16, v82
	v_and_b32_e32 v91, 0xffff0000, v82
	v_sub_f32_e32 v90, v92, v90
	v_sub_f32_e32 v91, v93, v91
	v_lshlrev_b32_e32 v92, 16, v83
	v_sub_f32_e32 v92, v94, v92
	v_mul_f32_e32 v94, 0x44000000, v90
	v_mul_f32_e32 v91, 0x44000000, v91
	v_mov_b32_e32 v90, v189
	v_cvt_pk_fp8_f32 v90, v94, v91
	v_and_b32_e32 v93, 0xffff0000, v83
	v_sub_f32_e32 v91, v95, v93
	v_cvt_pk_bf16_f32 v84, v110, v111
	v_mul_f32_e32 v92, 0x44000000, v92
	v_mul_f32_e32 v91, 0x44000000, v91
	v_cvt_pk_fp8_f32 v90, v92, v91 op_sel:[0,0,1]
	v_lshlrev_b32_e32 v91, 16, v84
	v_and_b32_e32 v92, 0xffff0000, v84
	v_sub_f32_e32 v91, v110, v91
	v_sub_f32_e32 v92, v111, v92
	v_mul_f32_e32 v95, 0x44000000, v91
	v_mul_f32_e32 v92, 0x44000000, v92
	v_mov_b32_e32 v91, v189
	v_cvt_pk_bf16_f32 v85, v156, v157
	v_cvt_pk_fp8_f32 v91, v95, v92
	v_lshlrev_b32_e32 v93, 16, v85
	v_and_b32_e32 v94, 0xffff0000, v85
	v_sub_f32_e32 v93, v156, v93
	v_sub_f32_e32 v92, v157, v94
	v_cvt_pk_bf16_f32 v86, v160, v161
	v_mul_f32_e32 v93, 0x44000000, v93
	v_mul_f32_e32 v92, 0x44000000, v92
	v_cvt_pk_fp8_f32 v91, v93, v92 op_sel:[0,0,1]
	v_lshlrev_b32_e32 v92, 16, v86
	v_and_b32_e32 v93, 0xffff0000, v86
	v_sub_f32_e32 v92, v160, v92
	v_sub_f32_e32 v93, v161, v93
	v_mul_f32_e32 v110, 0x44000000, v92
	v_mul_f32_e32 v93, 0x44000000, v93
	v_mov_b32_e32 v92, v189
	v_cvt_pk_bf16_f32 v87, v152, v153
	v_cvt_pk_fp8_f32 v92, v110, v93
	v_lshlrev_b32_e32 v94, 16, v87
	v_and_b32_e32 v95, 0xffff0000, v87
	v_sub_f32_e32 v94, v152, v94
	v_sub_f32_e32 v93, v153, v95
	v_cvt_pk_bf16_f32 v88, v80, v81
	v_mul_f32_e32 v94, 0x44000000, v94
	v_mul_f32_e32 v93, 0x44000000, v93
	v_cvt_pk_fp8_f32 v92, v94, v93 op_sel:[0,0,1]
	v_lshlrev_b32_e32 v93, 16, v88
	v_cvt_pk_bf16_f32 v89, v154, v155
	v_sub_f32_e32 v80, v80, v93
	v_and_b32_e32 v93, 0xffff0000, v88
	v_sub_f32_e32 v81, v81, v93
	v_lshlrev_b32_e32 v93, 16, v89
	v_sub_f32_e32 v94, v154, v93
	v_mul_f32_e32 v80, 0x44000000, v80
	v_mul_f32_e32 v81, 0x44000000, v81
	v_mov_b32_e32 v93, v189
	v_cvt_pk_fp8_f32 v93, v80, v81
	ds_bpermute_b32 v80, v241, v158
	v_and_b32_e32 v95, 0xffff0000, v89
	v_sub_f32_e32 v81, v155, v95
	v_mul_f32_e32 v94, 0x44000000, v94
	v_mul_f32_e32 v81, 0x44000000, v81
	s_waitcnt lgkmcnt(0)
	v_add_f32_e32 v80, v158, v80
	v_cvt_pk_fp8_f32 v93, v94, v81 op_sel:[0,0,1]
	ds_bpermute_b32 v81, v242, v80
	s_mov_b64 s[18:19], 0x8000
	v_lshl_add_u64 v[94:95], v[208:209], 0, s[18:19]
	global_store_dwordx4 v[216:217], v[82:85], off
	global_store_dwordx4 v[216:217], v[86:89], off offset:16
	global_store_dwordx4 v[94:95], v[90:93], off
	s_and_saveexec_b64 s[18:19], s[0:1]
	s_cbranch_execz .LBB0_264
	s_waitcnt lgkmcnt(0)
	v_add_f32_e32 v80, v80, v81
	global_atomic_add_f32 v[148:149], v80, off offset:128
; __device__ __forceinline__ float bflo(unsigned u) { return __uint_as_float(u << 16); }
; __device__ __forceinline__ float bfhi(unsigned u) { return __uint_as_float(u & 0xffff0000u); }
;     __device__ __forceinline__ void operator()(const AccT& acc, const Unit& u, int wr, int wc, int fr, int fq) const {
;     ...
;             if (idx + 4 < 8) { const size_t o = off0 + (size_t)(128 + (idx & 3) * 16) * DM;
;                 hr[idx & 3][0] = *(const u32x4*)(XB + o); hr[idx & 3][1] = *(const u32x4*)(XB + o + 8); lr[idx & 3] = *(const u32x4*)(XL + o); }
;             f32x4 x[4];
;             x[0] = (f32x4){bflo(h0.x), bfhi(h0.x), bflo(h0.y), bfhi(h0.y)} + un_lo8(l0.x);
;             x[1] = (f32x4){bflo(h0.z), bfhi(h0.z), bflo(h0.w), bfhi(h0.w)} + un_lo8(l0.y);
;             x[2] = (f32x4){bflo(h1.x), bfhi(h1.x), bflo(h1.y), bfhi(h1.y)} + un_lo8(l0.z);
;             x[3] = (f32x4){bflo(h1.z), bfhi(h1.z), bflo(h1.w), bfhi(h1.w)} + un_lo8(l0.w);
; #pragma unroll
;             for (int q = 0; q < 4; ++q) { x[q] = x[q] + scale * acc[ai][q >> 1][m][q & 1];
;                 s += (x[q][0] * x[q][0] + x[q][1] * x[q][1]) + (x[q][2] * x[q][2] + x[q][3] * x[q][3]); }
;             if (last) { float* p = OUT + off;
; #pragma unroll
;                 for (int q = 0; q < 4; ++q) *(f32x4*)(p + 4 * q) = x[q];
;             } else {
;                 u32x4 w0, w1, v0;
;                 w0.x = pk2(x[0][0], x[0][1]); w0.y = pk2(x[0][2], x[0][3]); w0.z = pk2(x[1][0], x[1][1]); w0.w = pk2(x[1][2], x[1][3]);
;                 w1.x = pk2(x[2][0], x[2][1]); w1.y = pk2(x[2][2], x[2][3]); w1.z = pk2(x[3][0], x[3][1]); w1.w = pk2(x[3][2], x[3][3]);
;                 v0.x = pk_lo8(x[0][0] - bflo(w0.x), x[0][1] - bfhi(w0.x), x[0][2] - bflo(w0.y), x[0][3] - bfhi(w0.y));
;                 v0.y = pk_lo8(x[1][0] - bflo(w0.z), x[1][1] - bfhi(w0.z), x[1][2] - bflo(w0.w), x[1][3] - bfhi(w0.w));
;                 v0.z = pk_lo8(x[2][0] - bflo(w1.x), x[2][1] - bfhi(w1.x), x[2][2] - bflo(w1.y), x[2][3] - bfhi(w1.y));
;                 v0.w = pk_lo8(x[3][0] - bflo(w1.z), x[3][1] - bfhi(w1.z), x[3][2] - bflo(w1.w), x[3][3] - bfhi(w1.w));
;                 u32x4* xb = (u32x4*)(XB + off); xb[0] = w0; xb[1] = w1;
;                 *(u32x4*)(XL + off) = v0;
;                 s += shx(s, LANE_, 16); s += shx(s, LANE_, 32);
;                 if (fq == 0) atomicAdd(ssq_next + row, s);
.LBB0_264:
	s_or_b64 exec, exec, s[18:19]
	v_add_co_u32_e32 v80, vcc, 0x58000, v214
	v_lshl_add_u64 v[92:93], v[214:215], 0, s[90:91]
	s_waitcnt lgkmcnt(0)
	v_addc_co_u32_e32 v81, vcc, 0, v215, vcc
	v_add_co_u32_e32 v84, vcc, 0x2c000, v208
	global_load_dwordx4 v[88:91], v[80:81], off nt
	s_nop 0
	global_load_dwordx4 v[80:83], v[92:93], off offset:16 nt
	v_addc_co_u32_e32 v85, vcc, 0, v209, vcc
	global_load_dwordx4 v[84:87], v[84:85], off nt
	v_cvt_f32_fp8_sdwa v152, v128 src0_sel:BYTE_2
	v_cvt_f32_fp8_sdwa v153, v128 src0_sel:BYTE_3
	v_lshlrev_b32_e32 v94, 16, v140
	v_and_b32_e32 v95, 0xffff0000, v140
	v_cvt_f32_fp8_e32 v110, v128
	v_cvt_f32_fp8_sdwa v111, v128 src0_sel:BYTE_1
	v_lshlrev_b32_e32 v140, 16, v141
	v_and_b32_e32 v141, 0xffff0000, v141
	v_pk_fma_f32 v[140:141], v[152:153], s[76:77], v[140:141] op_sel_hi:[1,0,1]
	v_cvt_f32_fp8_e32 v128, v129
	v_cvt_f32_fp8_sdwa v152, v129 src0_sel:BYTE_2
	v_cvt_f32_fp8_sdwa v153, v129 src0_sel:BYTE_3
	v_cvt_f32_fp8_sdwa v129, v129 src0_sel:BYTE_1
	v_cvt_f32_fp8_sdwa v154, v130 src0_sel:BYTE_2
	v_cvt_f32_fp8_sdwa v155, v130 src0_sel:BYTE_3
	v_pk_fma_f32 v[94:95], v[110:111], s[76:77], v[94:95] op_sel_hi:[1,0,1]
	v_lshlrev_b32_e32 v110, 16, v142
	v_and_b32_e32 v111, 0xffff0000, v142
	v_lshlrev_b32_e32 v142, 16, v143
	v_and_b32_e32 v143, 0xffff0000, v143
	v_pk_fma_f32 v[142:143], v[152:153], s[76:77], v[142:143] op_sel_hi:[1,0,1]
	v_pk_fma_f32 v[110:111], v[128:129], s[76:77], v[110:111] op_sel_hi:[1,0,1]
	v_lshlrev_b32_e32 v128, 16, v124
	v_and_b32_e32 v129, 0xffff0000, v124
	v_cvt_f32_fp8_e32 v152, v130
	v_cvt_f32_fp8_sdwa v153, v130 src0_sel:BYTE_1
	v_lshlrev_b32_e32 v124, 16, v125
	v_and_b32_e32 v125, 0xffff0000, v125
	v_pk_fma_f32 v[124:125], v[154:155], s[76:77], v[124:125] op_sel_hi:[1,0,1]
	v_cvt_f32_fp8_sdwa v154, v131 src0_sel:BYTE_2
	v_cvt_f32_fp8_sdwa v155, v131 src0_sel:BYTE_3
	v_pk_fma_f32 v[128:129], v[152:153], s[76:77], v[128:129] op_sel_hi:[1,0,1]
	v_lshlrev_b32_e32 v152, 16, v126
	v_and_b32_e32 v153, 0xffff0000, v126
	v_lshlrev_b32_e32 v126, 16, v127
	v_and_b32_e32 v127, 0xffff0000, v127
	v_pk_fma_f32 v[126:127], v[154:155], s[76:77], v[126:127] op_sel_hi:[1,0,1]
	v_pk_fma_f32 v[76:77], v[76:77], 0.5, v[94:95] op_sel_hi:[1,0,1]
	v_pk_fma_f32 v[78:79], v[78:79], 0.5, v[140:141] op_sel_hi:[1,0,1]
	v_pk_fma_f32 v[126:127], v[66:67], 0.5, v[126:127] op_sel_hi:[1,0,1]
	v_mul_f32_e32 v66, v77, v77
	v_mul_f32_e32 v67, v79, v79
	v_pk_fma_f32 v[94:95], v[72:73], 0.5, v[110:111] op_sel_hi:[1,0,1]
	v_pk_fma_f32 v[110:111], v[74:75], 0.5, v[142:143] op_sel_hi:[1,0,1]
	v_fmac_f32_e32 v66, v76, v76
	v_fmac_f32_e32 v67, v78, v78
	v_cvt_f32_fp8_e32 v130, v131
	v_cvt_f32_fp8_sdwa v131, v131 src0_sel:BYTE_1
	v_pk_fma_f32 v[128:129], v[68:69], 0.5, v[128:129] op_sel_hi:[1,0,1]
	v_add_f32_e32 v66, v66, v67
	v_mul_f32_e32 v67, v95, v95
	v_mul_f32_e32 v68, v111, v111
	v_fmac_f32_e32 v67, v94, v94
	v_fmac_f32_e32 v68, v110, v110
	v_pk_fma_f32 v[124:125], v[70:71], 0.5, v[124:125] op_sel_hi:[1,0,1]
	v_add_f32_e32 v67, v67, v68
	v_add_f32_e32 v66, v66, v67
	v_mul_f32_e32 v67, v129, v129
	v_mul_f32_e32 v68, v125, v125
	v_pk_fma_f32 v[130:131], v[130:131], s[76:77], v[152:153] op_sel_hi:[1,0,1]
	v_fmac_f32_e32 v67, v128, v128
	v_fmac_f32_e32 v68, v124, v124
	v_pk_fma_f32 v[64:65], v[64:65], 0.5, v[130:131] op_sel_hi:[1,0,1]
	v_add_f32_e32 v67, v67, v68
	v_add_f32_e32 v66, v66, v67
	v_mul_f32_e32 v67, v65, v65
	v_mul_f32_e32 v68, v127, v127
	v_fmac_f32_e32 v67, v64, v64
	v_fmac_f32_e32 v68, v126, v126
	v_add_f32_e32 v67, v67, v68
	v_add_f32_e32 v130, v66, v67
	v_cvt_pk_bf16_f32 v66, v76, v77
	v_cvt_pk_bf16_f32 v67, v78, v79
	v_lshlrev_b32_e32 v74, 16, v66
	v_and_b32_e32 v75, 0xffff0000, v66
	v_sub_f32_e32 v74, v76, v74
	v_sub_f32_e32 v75, v77, v75
	v_lshlrev_b32_e32 v76, 16, v67
	v_sub_f32_e32 v76, v78, v76
	v_mul_f32_e32 v78, 0x44000000, v74
	v_mul_f32_e32 v75, 0x44000000, v75
	v_mov_b32_e32 v74, v189
	v_cvt_pk_fp8_f32 v74, v78, v75
	v_and_b32_e32 v77, 0xffff0000, v67
	v_sub_f32_e32 v75, v79, v77
	v_cvt_pk_bf16_f32 v68, v94, v95
	v_mul_f32_e32 v76, 0x44000000, v76
	v_mul_f32_e32 v75, 0x44000000, v75
	v_cvt_pk_fp8_f32 v74, v76, v75 op_sel:[0,0,1]
	v_lshlrev_b32_e32 v75, 16, v68
	v_and_b32_e32 v76, 0xffff0000, v68
	v_sub_f32_e32 v75, v94, v75
	v_sub_f32_e32 v76, v95, v76
	v_mul_f32_e32 v79, 0x44000000, v75
	v_mul_f32_e32 v76, 0x44000000, v76
	v_mov_b32_e32 v75, v189
	v_cvt_pk_bf16_f32 v69, v110, v111
	v_cvt_pk_fp8_f32 v75, v79, v76
	v_lshlrev_b32_e32 v77, 16, v69
	v_and_b32_e32 v78, 0xffff0000, v69
	v_sub_f32_e32 v77, v110, v77
	v_sub_f32_e32 v76, v111, v78
	v_cvt_pk_bf16_f32 v70, v128, v129
	v_mul_f32_e32 v77, 0x44000000, v77
	v_mul_f32_e32 v76, 0x44000000, v76
	v_cvt_pk_fp8_f32 v75, v77, v76 op_sel:[0,0,1]
	v_lshlrev_b32_e32 v76, 16, v70
	v_and_b32_e32 v77, 0xffff0000, v70
	v_sub_f32_e32 v76, v128, v76
	v_sub_f32_e32 v77, v129, v77
	v_mul_f32_e32 v94, 0x44000000, v76
	v_mul_f32_e32 v77, 0x44000000, v77
	v_mov_b32_e32 v76, v189
	v_cvt_pk_bf16_f32 v71, v124, v125
	v_cvt_pk_fp8_f32 v76, v94, v77
	v_lshlrev_b32_e32 v78, 16, v71
	v_and_b32_e32 v79, 0xffff0000, v71
	v_sub_f32_e32 v78, v124, v78
	v_sub_f32_e32 v77, v125, v79
	v_cvt_pk_bf16_f32 v72, v64, v65
	v_mul_f32_e32 v78, 0x44000000, v78
	v_mul_f32_e32 v77, 0x44000000, v77
	v_cvt_pk_fp8_f32 v76, v78, v77 op_sel:[0,0,1]
	v_lshlrev_b32_e32 v77, 16, v72
	v_cvt_pk_bf16_f32 v73, v126, v127
	v_sub_f32_e32 v64, v64, v77
	v_and_b32_e32 v77, 0xffff0000, v72
	v_sub_f32_e32 v65, v65, v77
	v_lshlrev_b32_e32 v77, 16, v73
	v_sub_f32_e32 v78, v126, v77
	v_mul_f32_e32 v64, 0x44000000, v64
	v_mul_f32_e32 v65, 0x44000000, v65
	v_mov_b32_e32 v77, v189
	v_cvt_pk_fp8_f32 v77, v64, v65
	ds_bpermute_b32 v64, v241, v130
	v_and_b32_e32 v79, 0xffff0000, v73
	v_sub_f32_e32 v65, v127, v79
	v_mul_f32_e32 v78, 0x44000000, v78
	v_mul_f32_e32 v65, 0x44000000, v65
	s_waitcnt lgkmcnt(0)
	v_add_f32_e32 v64, v130, v64
	v_cvt_pk_fp8_f32 v77, v78, v65 op_sel:[0,0,1]
	ds_bpermute_b32 v65, v242, v64
	s_mov_b64 s[18:19], 0xc000
	v_lshl_add_u64 v[78:79], v[208:209], 0, s[18:19]
	global_store_dwordx4 v[212:213], v[66:69], off
	global_store_dwordx4 v[212:213], v[70:73], off offset:16
	global_store_dwordx4 v[78:79], v[74:77], off
	s_and_saveexec_b64 s[18:19], s[0:1]
	s_cbranch_execz .LBB0_266
	s_waitcnt lgkmcnt(0)
	v_add_f32_e32 v64, v64, v65
	global_atomic_add_f32 v[148:149], v64, off offset:192

; __device__ __forceinline__ float bflo(unsigned u) { return __uint_as_float(u << 16); }
; __device__ __forceinline__ float bfhi(unsigned u) { return __uint_as_float(u & 0xffff0000u); }
; #define EPI_SCHED() do {} while (0)
; __device__ __forceinline__ f32x4 un_lo8(unsigned w) { return (f32x4){__builtin_amdgcn_cvt_f32_fp8((int)w, 0), __builtin_amdgcn_cvt_f32_fp8((int)w, 1), __builtin_amdgcn_cvt_f32_fp8((int)w, 2), __builtin_amdgcn_cvt_f32_fp8((int)w, 3)} * (1.f / 512.f); }
;     __device__ __forceinline__ void operator()(const AccT& acc, const Unit& u, int wr, int wc, int fr, int fq) const {
;         const int row0 = u.pm * 256 + wr * 64 + fr, col0 = u.pn * 256 + wc * 64 + 16 * fq;
;         const size_t off0 = (size_t)row0 * DM + col0;
;         u32x4 hr[4][2], lr[4];
; #pragma unroll
;         for (int i = 0; i < 4; ++i) { const size_t o = off0 + (size_t)(i * 16) * DM; hr[i][0] = *(const u32x4*)(XB + o); hr[i][1] = *(const u32x4*)(XB + o + 8); lr[i] = *(const u32x4*)(XL + o); }
;         EPI_SCHED();
; #pragma unroll
;         for (int idx = 0; idx < 8; ++idx) {
;             const int ai = idx >> 2, m = idx & 3, rofs = ai * 128 + m * 16;
;             const int row = row0 + rofs; float s = 0.f;
;             const size_t off = off0 + (size_t)rofs * DM;
;             const u32x4 h0 = hr[idx & 3][0], h1 = hr[idx & 3][1], l0 = lr[idx & 3];
;             if (idx + 4 < 8) { const size_t o = off0 + (size_t)(128 + (idx & 3) * 16) * DM;
;                 hr[idx & 3][0] = *(const u32x4*)(XB + o); hr[idx & 3][1] = *(const u32x4*)(XB + o + 8); lr[idx & 3] = *(const u32x4*)(XL + o); }
;             f32x4 x[4];
;             x[0] = (f32x4){bflo(h0.x), bfhi(h0.x), bflo(h0.y), bfhi(h0.y)} + un_lo8(l0.x);
;             x[1] = (f32x4){bflo(h0.z), bfhi(h0.z), bflo(h0.w), bfhi(h0.w)} + un_lo8(l0.y);
;             x[2] = (f32x4){bflo(h1.x), bfhi(h1.x), bflo(h1.y), bfhi(h1.y)} + un_lo8(l0.z);
;             x[3] = (f32x4){bflo(h1.z), bfhi(h1.z), bflo(h1.w), bfhi(h1.w)} + un_lo8(l0.w);
; #pragma unroll
;             for (int q = 0; q < 4; ++q) { x[q] = x[q] + scale * acc[ai][q >> 1][m][q & 1];
;                 s += (x[q][0] * x[q][0] + x[q][1] * x[q][1]) + (x[q][2] * x[q][2] + x[q][3] * x[q][3]); }
.LBB0_896:
	v_lshl_add_u32 v220, s44, 8, v239
	v_lshl_or_b32 v112, s43, 8, v243
	v_ashrrev_i32_e32 v221, 31, v220
	v_lshlrev_b64 v[114:115], 10, v[220:221]
	v_ashrrev_i32_e32 v113, 31, v112
	v_lshl_add_u64 v[112:113], v[114:115], 0, v[112:113]
	v_lshl_add_u64 v[214:215], v[112:113], 1, s[8:9]
	v_lshl_add_u64 v[208:209], s[12:13], 0, v[112:113]
	global_load_dwordx4 v[180:183], v[214:215], off offset:16 nt
	global_load_dwordx4 v[184:187], v[214:215], off nt
	global_load_dwordx4 v[176:179], v[208:209], off nt
	v_add_co_u32_e32 v112, vcc, s85, v214
	s_mov_b64 s[24:25], 0x8000
	s_nop 0
	v_addc_co_u32_e32 v113, vcc, 0, v215, vcc
	s_movk_i32 s17, 0x4000
	v_lshl_add_u64 v[218:219], v[214:215], 0, s[24:25]
	global_load_dwordx4 v[172:175], v[112:113], off nt
	global_load_dwordx4 v[164:167], v[218:219], off offset:16 nt
	v_add_co_u32_e32 v112, vcc, s17, v208
	v_lshl_add_u64 v[216:217], v[214:215], 0, s[56:57]
	s_nop 0
	v_addc_co_u32_e32 v113, vcc, 0, v209, vcc
	global_load_dwordx4 v[168:171], v[112:113], off nt
	v_add_co_u32_e32 v112, vcc, s84, v214
	s_mov_b64 s[24:25], 0x18000
	s_nop 0
	v_addc_co_u32_e32 v113, vcc, 0, v215, vcc
	global_load_dwordx4 v[160:163], v[112:113], off nt
	global_load_dwordx4 v[152:155], v[216:217], off offset:16 nt
	v_add_co_u32_e32 v112, vcc, s85, v208
	s_mov_b32 s17, 0xc000
	s_nop 0
	v_addc_co_u32_e32 v113, vcc, 0, v209, vcc
	global_load_dwordx4 v[156:159], v[112:113], off nt
	v_add_co_u32_e32 v112, vcc, s83, v214
	v_lshl_add_u64 v[212:213], v[214:215], 0, s[24:25]
	s_nop 0
	v_addc_co_u32_e32 v113, vcc, 0, v215, vcc
	global_load_dwordx4 v[140:143], v[112:113], off nt
	global_load_dwordx4 v[124:127], v[212:213], off offset:16 nt
	v_add_co_u32_e32 v112, vcc, s17, v208
	s_mov_b32 s17, 0x20000
	s_nop 0
	v_addc_co_u32_e32 v113, vcc, 0, v209, vcc
	global_load_dwordx4 v[128:131], v[112:113], off nt
	v_add_co_u32_e32 v112, vcc, s82, v214
	s_mov_b64 s[24:25], 0x40000
	s_nop 0
	v_addc_co_u32_e32 v113, vcc, 0, v215, vcc
	v_add_co_u32_e32 v120, vcc, s17, v208
	v_lshl_add_u64 v[210:211], v[214:215], 0, s[24:25]
	s_nop 0
	v_addc_co_u32_e32 v121, vcc, 0, v209, vcc
	global_load_dwordx4 v[116:119], v[112:113], off nt
	s_nop 0
	global_load_dwordx4 v[112:115], v[210:211], off offset:16 nt
	s_waitcnt vmcnt(0)
	v_lshlrev_b32_e32 v222, 16, v184
	global_load_dwordx4 v[120:123], v[120:121], off nt
	v_cvt_f32_fp8_sdwa v230, v176 src0_sel:BYTE_2
	v_cvt_f32_fp8_sdwa v231, v176 src0_sel:BYTE_3
	v_and_b32_e32 v223, 0xffff0000, v184
	v_lshlrev_b32_e32 v184, 16, v185
	v_and_b32_e32 v185, 0xffff0000, v185
	v_cvt_f32_fp8_e32 v228, v176
	v_cvt_f32_fp8_sdwa v229, v176 src0_sel:BYTE_1
	v_pk_fma_f32 v[184:185], v[230:231], s[76:77], v[184:185] op_sel_hi:[1,0,1]
	v_cvt_f32_fp8_e32 v230, v177
	v_cvt_f32_fp8_sdwa v231, v177 src0_sel:BYTE_1
	v_cvt_f32_fp8_sdwa v176, v177 src0_sel:BYTE_2
	v_cvt_f32_fp8_sdwa v177, v177 src0_sel:BYTE_3
	v_cvt_f32_fp8_sdwa v232, v178 src0_sel:BYTE_2
	v_cvt_f32_fp8_sdwa v233, v178 src0_sel:BYTE_3
	v_pk_fma_f32 v[222:223], v[228:229], s[76:77], v[222:223] op_sel_hi:[1,0,1]
	v_lshlrev_b32_e32 v228, 16, v186
	v_and_b32_e32 v229, 0xffff0000, v186
	v_lshlrev_b32_e32 v186, 16, v187
	v_and_b32_e32 v187, 0xffff0000, v187
	v_pk_fma_f32 v[176:177], v[176:177], s[76:77], v[186:187] op_sel_hi:[1,0,1]
	v_pk_fma_f32 v[186:187], v[230:231], s[76:77], v[228:229] op_sel_hi:[1,0,1]
	v_lshlrev_b32_e32 v228, 16, v180
	v_and_b32_e32 v229, 0xffff0000, v180
	v_lshlrev_b32_e32 v180, 16, v181
	v_and_b32_e32 v181, 0xffff0000, v181
	v_cvt_f32_fp8_e32 v230, v178
	v_cvt_f32_fp8_sdwa v231, v178 src0_sel:BYTE_1
	v_pk_fma_f32 v[180:181], v[232:233], s[76:77], v[180:181] op_sel_hi:[1,0,1]
	v_cvt_f32_fp8_e32 v232, v179
	v_cvt_f32_fp8_sdwa v233, v179 src0_sel:BYTE_1
	v_cvt_f32_fp8_sdwa v178, v179 src0_sel:BYTE_2
	v_cvt_f32_fp8_sdwa v179, v179 src0_sel:BYTE_3
	v_pk_fma_f32 v[228:229], v[230:231], s[76:77], v[228:229] op_sel_hi:[1,0,1]
	v_lshlrev_b32_e32 v230, 16, v182
	v_and_b32_e32 v231, 0xffff0000, v182
	v_lshlrev_b32_e32 v182, 16, v183
	v_and_b32_e32 v183, 0xffff0000, v183
	v_pk_fma_f32 v[178:179], v[178:179], s[76:77], v[182:183] op_sel_hi:[1,0,1]
	v_pk_fma_f32 v[182:183], v[232:233], s[76:77], v[230:231] op_sel_hi:[1,0,1]
	v_pk_add_f32 v[148:149], v[148:149], v[222:223]
	v_pk_add_f32 v[150:151], v[150:151], v[184:185]
	v_pk_add_f32 v[182:183], v[132:133], v[182:183]
	v_mul_f32_e32 v132, v149, v149
	v_mul_f32_e32 v133, v151, v151
	v_pk_add_f32 v[184:185], v[144:145], v[186:187]
	v_pk_add_f32 v[146:147], v[146:147], v[176:177]
	v_fmac_f32_e32 v132, v148, v148
	v_fmac_f32_e32 v133, v150, v150
	v_pk_add_f32 v[178:179], v[134:135], v[178:179]
	v_add_f32_e32 v132, v132, v133
	v_mul_f32_e32 v133, v185, v185
	v_mul_f32_e32 v134, v147, v147
	v_fmac_f32_e32 v133, v184, v184
	v_fmac_f32_e32 v134, v146, v146
	v_pk_add_f32 v[176:177], v[136:137], v[228:229]
	v_pk_add_f32 v[180:181], v[138:139], v[180:181]
	v_add_f32_e32 v133, v133, v134
	v_add_f32_e32 v132, v132, v133
	v_mul_f32_e32 v133, v177, v177
	v_mul_f32_e32 v134, v181, v181
	v_fmac_f32_e32 v133, v176, v176
	v_fmac_f32_e32 v134, v180, v180
	v_add_f32_e32 v133, v133, v134
	v_add_f32_e32 v132, v132, v133
	v_mul_f32_e32 v133, v183, v183
	v_mul_f32_e32 v134, v179, v179
	v_fmac_f32_e32 v133, v182, v182
	v_fmac_f32_e32 v134, v178, v178
	v_add_f32_e32 v133, v133, v134
	v_add_f32_e32 v186, v132, v133
	v_cvt_pk_bf16_f32 v132, v148, v149
	v_cvt_pk_bf16_f32 v133, v150, v151
	v_lshlrev_b32_e32 v144, 16, v132
	v_and_b32_e32 v145, 0xffff0000, v132
	v_sub_f32_e32 v144, v148, v144
	v_sub_f32_e32 v145, v149, v145
	v_lshlrev_b32_e32 v148, 16, v133
	v_sub_f32_e32 v148, v150, v148
	v_mul_f32_e32 v150, 0x44000000, v144
; __device__ __forceinline__ float bflo(unsigned u) { return __uint_as_float(u << 16); }
; __device__ __forceinline__ float bfhi(unsigned u) { return __uint_as_float(u & 0xffff0000u); }
;     __device__ __forceinline__ void operator()(const AccT& acc, const Unit& u, int wr, int wc, int fr, int fq) const {
;     ...
;             if (idx + 4 < 8) { const size_t o = off0 + (size_t)(128 + (idx & 3) * 16) * DM;
;                 hr[idx & 3][0] = *(const u32x4*)(XB + o); hr[idx & 3][1] = *(const u32x4*)(XB + o + 8); lr[idx & 3] = *(const u32x4*)(XL + o); }
;             f32x4 x[4];
;             x[0] = (f32x4){bflo(h0.x), bfhi(h0.x), bflo(h0.y), bfhi(h0.y)} + un_lo8(l0.x);
;             x[1] = (f32x4){bflo(h0.z), bfhi(h0.z), bflo(h0.w), bfhi(h0.w)} + un_lo8(l0.y);
;             x[2] = (f32x4){bflo(h1.x), bfhi(h1.x), bflo(h1.y), bfhi(h1.y)} + un_lo8(l0.z);
;             x[3] = (f32x4){bflo(h1.z), bfhi(h1.z), bflo(h1.w), bfhi(h1.w)} + un_lo8(l0.w);
; #pragma unroll
;             for (int q = 0; q < 4; ++q) { x[q] = x[q] + scale * acc[ai][q >> 1][m][q & 1];
;                 s += (x[q][0] * x[q][0] + x[q][1] * x[q][1]) + (x[q][2] * x[q][2] + x[q][3] * x[q][3]); }
;             if (last) { float* p = OUT + off;
; #pragma unroll
;                 for (int q = 0; q < 4; ++q) *(f32x4*)(p + 4 * q) = x[q];
;             } else {
;                 u32x4 w0, w1, v0;
;                 w0.x = pk2(x[0][0], x[0][1]); w0.y = pk2(x[0][2], x[0][3]); w0.z = pk2(x[1][0], x[1][1]); w0.w = pk2(x[1][2], x[1][3]);
;                 w1.x = pk2(x[2][0], x[2][1]); w1.y = pk2(x[2][2], x[2][3]); w1.z = pk2(x[3][0], x[3][1]); w1.w = pk2(x[3][2], x[3][3]);
;                 v0.x = pk_lo8(x[0][0] - bflo(w0.x), x[0][1] - bfhi(w0.x), x[0][2] - bflo(w0.y), x[0][3] - bfhi(w0.y));
;                 v0.y = pk_lo8(x[1][0] - bflo(w0.z), x[1][1] - bfhi(w0.z), x[1][2] - bflo(w0.w), x[1][3] - bfhi(w0.w));
;                 v0.z = pk_lo8(x[2][0] - bflo(w1.x), x[2][1] - bfhi(w1.x), x[2][2] - bflo(w1.y), x[2][3] - bfhi(w1.y));
;                 v0.w = pk_lo8(x[3][0] - bflo(w1.z), x[3][1] - bfhi(w1.z), x[3][2] - bflo(w1.w), x[3][3] - bfhi(w1.w));
;                 u32x4* xb = (u32x4*)(XB + off); xb[0] = w0; xb[1] = w1;
;                 *(u32x4*)(XL + off) = v0;
;                 s += shx(s, LANE_, 16); s += shx(s, LANE_, 32);
;                 if (fq == 0) atomicAdd(ssq_next + row, s);
	v_mul_f32_e32 v145, 0x44000000, v145
	v_mov_b32_e32 v144, v189
	v_cvt_pk_fp8_f32 v144, v150, v145
	v_and_b32_e32 v149, 0xffff0000, v133
	v_sub_f32_e32 v149, v151, v149
	v_cvt_pk_bf16_f32 v134, v184, v185
	v_cvt_pk_bf16_f32 v135, v146, v147
	v_mul_f32_e32 v145, 0x44000000, v148
	v_mul_f32_e32 v148, 0x44000000, v149
	v_cvt_pk_fp8_f32 v144, v145, v148 op_sel:[0,0,1]
	v_lshlrev_b32_e32 v145, 16, v134
	v_and_b32_e32 v148, 0xffff0000, v134
	v_lshlrev_b32_e32 v149, 16, v135
	v_sub_f32_e32 v145, v184, v145
	v_sub_f32_e32 v148, v185, v148
	v_sub_f32_e32 v146, v146, v149
	v_and_b32_e32 v149, 0xffff0000, v135
	v_sub_f32_e32 v147, v147, v149
	v_mul_f32_e32 v149, 0x44000000, v145
	v_mul_f32_e32 v148, 0x44000000, v148
	v_mov_b32_e32 v145, v189
	v_cvt_pk_fp8_f32 v145, v149, v148
	v_cvt_pk_bf16_f32 v136, v176, v177
	v_mul_f32_e32 v146, 0x44000000, v146
	v_mul_f32_e32 v147, 0x44000000, v147
	v_cvt_pk_fp8_f32 v145, v146, v147 op_sel:[0,0,1]
	v_lshlrev_b32_e32 v146, 16, v136
	v_and_b32_e32 v147, 0xffff0000, v136
	v_sub_f32_e32 v146, v176, v146
	v_sub_f32_e32 v147, v177, v147
	v_mul_f32_e32 v150, 0x44000000, v146
	v_mul_f32_e32 v147, 0x44000000, v147
	v_mov_b32_e32 v146, v189
	v_cvt_pk_bf16_f32 v137, v180, v181
	v_cvt_pk_fp8_f32 v146, v150, v147
	v_lshlrev_b32_e32 v148, 16, v137
	v_and_b32_e32 v149, 0xffff0000, v137
	v_sub_f32_e32 v148, v180, v148
	v_sub_f32_e32 v149, v181, v149
	v_cvt_pk_bf16_f32 v138, v182, v183
	v_mul_f32_e32 v147, 0x44000000, v148
	v_mul_f32_e32 v148, 0x44000000, v149
	v_cvt_pk_fp8_f32 v146, v147, v148 op_sel:[0,0,1]
	v_lshlrev_b32_e32 v147, 16, v138
	v_and_b32_e32 v148, 0xffff0000, v138
	v_sub_f32_e32 v147, v182, v147
	v_sub_f32_e32 v148, v183, v148
	v_mul_f32_e32 v151, 0x44000000, v147
	v_mul_f32_e32 v148, 0x44000000, v148
	v_mov_b32_e32 v147, v189
	v_cvt_pk_bf16_f32 v139, v178, v179
	v_cvt_pk_fp8_f32 v147, v151, v148
	v_lshlrev_b32_e32 v149, 16, v139
	v_and_b32_e32 v150, 0xffff0000, v139
	v_sub_f32_e32 v149, v178, v149
	v_sub_f32_e32 v150, v179, v150
	v_mul_f32_e32 v148, 0x44000000, v149
	v_mul_f32_e32 v149, 0x44000000, v150
	v_cvt_pk_fp8_f32 v147, v148, v149 op_sel:[0,0,1]
	global_store_dwordx4 v[214:215], v[132:135], off
	global_store_dwordx4 v[214:215], v[136:139], off offset:16
	global_store_dwordx4 v[208:209], v[144:147], off
	ds_bpermute_b32 v132, v241, v186
	v_lshl_add_u64 v[148:149], v[220:221], 2, s[10:11]
	s_waitcnt lgkmcnt(0)
	v_add_f32_e32 v132, v186, v132
	ds_bpermute_b32 v133, v242, v132
	s_and_saveexec_b64 s[24:25], s[0:1]
	s_cbranch_execz .LBB0_898
	s_waitcnt lgkmcnt(0)
	v_add_f32_e32 v132, v132, v133
	global_atomic_add_f32 v[148:149], v132, off
.LBB0_898:
	s_or_b64 exec, exec, s[24:25]
	v_add_co_u32_e32 v132, vcc, 0x48000, v214
	s_mov_b64 s[24:25], 0x48000
	s_waitcnt lgkmcnt(0)
	v_addc_co_u32_e32 v133, vcc, 0, v215, vcc
	v_add_co_u32_e32 v136, vcc, 0x24000, v208
	v_lshl_add_u64 v[150:151], v[214:215], 0, s[24:25]
	s_nop 0
	v_addc_co_u32_e32 v137, vcc, 0, v209, vcc
	global_load_dwordx4 v[144:147], v[132:133], off nt
	s_nop 0
	global_load_dwordx4 v[132:135], v[150:151], off offset:16 nt
	v_cvt_f32_fp8_sdwa v180, v168 src0_sel:BYTE_2
	global_load_dwordx4 v[136:139], v[136:137], off nt
	v_cvt_f32_fp8_sdwa v181, v168 src0_sel:BYTE_3
	v_lshlrev_b32_e32 v176, 16, v172
	v_and_b32_e32 v177, 0xffff0000, v172
	v_cvt_f32_fp8_e32 v178, v168
	v_cvt_f32_fp8_sdwa v179, v168 src0_sel:BYTE_1
	v_lshlrev_b32_e32 v172, 16, v173
	v_and_b32_e32 v173, 0xffff0000, v173
	v_pk_fma_f32 v[172:173], v[180:181], s[76:77], v[172:173] op_sel_hi:[1,0,1]
	v_cvt_f32_fp8_e32 v168, v169
	v_cvt_f32_fp8_sdwa v180, v169 src0_sel:BYTE_2
	v_cvt_f32_fp8_sdwa v181, v169 src0_sel:BYTE_3
	v_cvt_f32_fp8_sdwa v169, v169 src0_sel:BYTE_1
	v_cvt_f32_fp8_sdwa v182, v170 src0_sel:BYTE_2
	v_cvt_f32_fp8_sdwa v183, v170 src0_sel:BYTE_3
	v_pk_fma_f32 v[176:177], v[178:179], s[76:77], v[176:177] op_sel_hi:[1,0,1]
	v_lshlrev_b32_e32 v178, 16, v174
	v_and_b32_e32 v179, 0xffff0000, v174
	v_lshlrev_b32_e32 v174, 16, v175
	v_and_b32_e32 v175, 0xffff0000, v175
	v_pk_fma_f32 v[174:175], v[180:181], s[76:77], v[174:175] op_sel_hi:[1,0,1]
	v_pk_fma_f32 v[168:169], v[168:169], s[76:77], v[178:179] op_sel_hi:[1,0,1]
	v_lshlrev_b32_e32 v178, 16, v164
	v_and_b32_e32 v179, 0xffff0000, v164
	v_cvt_f32_fp8_e32 v180, v170
	v_cvt_f32_fp8_sdwa v181, v170 src0_sel:BYTE_1
	v_lshlrev_b32_e32 v164, 16, v165
	v_and_b32_e32 v165, 0xffff0000, v165
	v_pk_fma_f32 v[164:165], v[182:183], s[76:77], v[164:165] op_sel_hi:[1,0,1]
	v_cvt_f32_fp8_sdwa v182, v171 src0_sel:BYTE_2
	v_cvt_f32_fp8_sdwa v183, v171 src0_sel:BYTE_3
	v_pk_fma_f32 v[178:179], v[180:181], s[76:77], v[178:179] op_sel_hi:[1,0,1]
	v_lshlrev_b32_e32 v180, 16, v166
	v_and_b32_e32 v181, 0xffff0000, v166
	v_lshlrev_b32_e32 v166, 16, v167
	v_and_b32_e32 v167, 0xffff0000, v167
	v_pk_fma_f32 v[166:167], v[182:183], s[76:77], v[166:167] op_sel_hi:[1,0,1]
	v_pk_add_f32 v[108:109], v[108:109], v[176:177]
	v_pk_add_f32 v[110:111], v[110:111], v[172:173]
	v_pk_add_f32 v[166:167], v[98:99], v[166:167]
	v_mul_f32_e32 v98, v109, v109
	v_mul_f32_e32 v99, v111, v111
	v_pk_add_f32 v[168:169], v[104:105], v[168:169]
	v_pk_add_f32 v[172:173], v[106:107], v[174:175]
	v_fmac_f32_e32 v98, v108, v108
	v_fmac_f32_e32 v99, v110, v110
	v_cvt_f32_fp8_e32 v170, v171
	v_cvt_f32_fp8_sdwa v171, v171 src0_sel:BYTE_1
	v_pk_add_f32 v[174:175], v[100:101], v[178:179]
	v_add_f32_e32 v98, v98, v99
	v_mul_f32_e32 v99, v169, v169
	v_mul_f32_e32 v100, v173, v173
	v_fmac_f32_e32 v99, v168, v168
	v_fmac_f32_e32 v100, v172, v172
	v_pk_add_f32 v[164:165], v[102:103], v[164:165]
	v_add_f32_e32 v99, v99, v100
	v_add_f32_e32 v98, v98, v99
	v_mul_f32_e32 v99, v175, v175
; __device__ __forceinline__ float bflo(unsigned u) { return __uint_as_float(u << 16); }
; __device__ __forceinline__ float bfhi(unsigned u) { return __uint_as_float(u & 0xffff0000u); }
;     __device__ __forceinline__ void operator()(const AccT& acc, const Unit& u, int wr, int wc, int fr, int fq) const {
;     ...
;             if (idx + 4 < 8) { const size_t o = off0 + (size_t)(128 + (idx & 3) * 16) * DM;
;                 hr[idx & 3][0] = *(const u32x4*)(XB + o); hr[idx & 3][1] = *(const u32x4*)(XB + o + 8); lr[idx & 3] = *(const u32x4*)(XL + o); }
;             f32x4 x[4];
;             x[0] = (f32x4){bflo(h0.x), bfhi(h0.x), bflo(h0.y), bfhi(h0.y)} + un_lo8(l0.x);
;             x[1] = (f32x4){bflo(h0.z), bfhi(h0.z), bflo(h0.w), bfhi(h0.w)} + un_lo8(l0.y);
;             x[2] = (f32x4){bflo(h1.x), bfhi(h1.x), bflo(h1.y), bfhi(h1.y)} + un_lo8(l0.z);
;             x[3] = (f32x4){bflo(h1.z), bfhi(h1.z), bflo(h1.w), bfhi(h1.w)} + un_lo8(l0.w);
; #pragma unroll
;             for (int q = 0; q < 4; ++q) { x[q] = x[q] + scale * acc[ai][q >> 1][m][q & 1];
;                 s += (x[q][0] * x[q][0] + x[q][1] * x[q][1]) + (x[q][2] * x[q][2] + x[q][3] * x[q][3]); }
;             if (last) { float* p = OUT + off;
; #pragma unroll
;                 for (int q = 0; q < 4; ++q) *(f32x4*)(p + 4 * q) = x[q];
;             } else {
;                 u32x4 w0, w1, v0;
;                 w0.x = pk2(x[0][0], x[0][1]); w0.y = pk2(x[0][2], x[0][3]); w0.z = pk2(x[1][0], x[1][1]); w0.w = pk2(x[1][2], x[1][3]);
;                 w1.x = pk2(x[2][0], x[2][1]); w1.y = pk2(x[2][2], x[2][3]); w1.z = pk2(x[3][0], x[3][1]); w1.w = pk2(x[3][2], x[3][3]);
;                 v0.x = pk_lo8(x[0][0] - bflo(w0.x), x[0][1] - bfhi(w0.x), x[0][2] - bflo(w0.y), x[0][3] - bfhi(w0.y));
;                 v0.y = pk_lo8(x[1][0] - bflo(w0.z), x[1][1] - bfhi(w0.z), x[1][2] - bflo(w0.w), x[1][3] - bfhi(w0.w));
;                 v0.z = pk_lo8(x[2][0] - bflo(w1.x), x[2][1] - bfhi(w1.x), x[2][2] - bflo(w1.y), x[2][3] - bfhi(w1.y));
;                 v0.w = pk_lo8(x[3][0] - bflo(w1.z), x[3][1] - bfhi(w1.z), x[3][2] - bflo(w1.w), x[3][3] - bfhi(w1.w));
;                 u32x4* xb = (u32x4*)(XB + off); xb[0] = w0; xb[1] = w1;
;                 *(u32x4*)(XL + off) = v0;
;                 s += shx(s, LANE_, 16); s += shx(s, LANE_, 32);
;                 if (fq == 0) atomicAdd(ssq_next + row, s);
	v_mul_f32_e32 v100, v165, v165
	v_pk_fma_f32 v[170:171], v[170:171], s[76:77], v[180:181] op_sel_hi:[1,0,1]
	v_fmac_f32_e32 v99, v174, v174
	v_fmac_f32_e32 v100, v164, v164
	v_pk_add_f32 v[96:97], v[96:97], v[170:171]
	v_add_f32_e32 v99, v99, v100
	v_add_f32_e32 v98, v98, v99
	v_mul_f32_e32 v99, v97, v97
	v_mul_f32_e32 v100, v167, v167
	v_fmac_f32_e32 v99, v96, v96
	v_fmac_f32_e32 v100, v166, v166
	v_add_f32_e32 v99, v99, v100
	v_add_f32_e32 v170, v98, v99
	v_cvt_pk_bf16_f32 v98, v108, v109
	v_cvt_pk_bf16_f32 v99, v110, v111
	v_lshlrev_b32_e32 v106, 16, v98
	v_and_b32_e32 v107, 0xffff0000, v98
	v_sub_f32_e32 v106, v108, v106
	v_sub_f32_e32 v107, v109, v107
	v_lshlrev_b32_e32 v108, 16, v99
	v_sub_f32_e32 v108, v110, v108
	v_mul_f32_e32 v110, 0x44000000, v106
	v_mul_f32_e32 v107, 0x44000000, v107
	v_mov_b32_e32 v106, v189
	v_cvt_pk_fp8_f32 v106, v110, v107
	v_and_b32_e32 v109, 0xffff0000, v99
	v_sub_f32_e32 v107, v111, v109
	v_cvt_pk_bf16_f32 v100, v168, v169
	v_mul_f32_e32 v108, 0x44000000, v108
	v_mul_f32_e32 v107, 0x44000000, v107
	v_cvt_pk_fp8_f32 v106, v108, v107 op_sel:[0,0,1]
	v_lshlrev_b32_e32 v107, 16, v100
	v_and_b32_e32 v108, 0xffff0000, v100
	v_sub_f32_e32 v107, v168, v107
	v_sub_f32_e32 v108, v169, v108
	v_mul_f32_e32 v111, 0x44000000, v107
	v_mul_f32_e32 v108, 0x44000000, v108
	v_mov_b32_e32 v107, v189
	v_cvt_pk_bf16_f32 v101, v172, v173
	v_cvt_pk_fp8_f32 v107, v111, v108
	v_lshlrev_b32_e32 v109, 16, v101
	v_and_b32_e32 v110, 0xffff0000, v101
	v_sub_f32_e32 v109, v172, v109
	v_sub_f32_e32 v108, v173, v110
	v_cvt_pk_bf16_f32 v102, v174, v175
	v_mul_f32_e32 v109, 0x44000000, v109
	v_mul_f32_e32 v108, 0x44000000, v108
	v_cvt_pk_bf16_f32 v103, v164, v165
	v_cvt_pk_fp8_f32 v107, v109, v108 op_sel:[0,0,1]
	v_lshlrev_b32_e32 v108, 16, v102
	v_and_b32_e32 v109, 0xffff0000, v102
	v_sub_f32_e32 v108, v174, v108
	v_sub_f32_e32 v109, v175, v109
	v_lshlrev_b32_e32 v110, 16, v103
	v_sub_f32_e32 v110, v164, v110
	v_mul_f32_e32 v164, 0x44000000, v108
	v_mul_f32_e32 v109, 0x44000000, v109
	v_mov_b32_e32 v108, v189
	v_cvt_pk_fp8_f32 v108, v164, v109
	v_and_b32_e32 v111, 0xffff0000, v103
	v_sub_f32_e32 v109, v165, v111
	v_cvt_pk_bf16_f32 v104, v96, v97
	v_mul_f32_e32 v110, 0x44000000, v110
	v_mul_f32_e32 v109, 0x44000000, v109
	v_cvt_pk_fp8_f32 v108, v110, v109 op_sel:[0,0,1]
	v_lshlrev_b32_e32 v109, 16, v104
	v_cvt_pk_bf16_f32 v105, v166, v167
	v_sub_f32_e32 v96, v96, v109
	v_and_b32_e32 v109, 0xffff0000, v104
	v_sub_f32_e32 v97, v97, v109
	v_lshlrev_b32_e32 v109, 16, v105
	v_sub_f32_e32 v110, v166, v109
	v_mul_f32_e32 v96, 0x44000000, v96
	v_mul_f32_e32 v97, 0x44000000, v97
	v_mov_b32_e32 v109, v189
	v_cvt_pk_fp8_f32 v109, v96, v97
	ds_bpermute_b32 v96, v241, v170
	v_and_b32_e32 v111, 0xffff0000, v105
	v_sub_f32_e32 v97, v167, v111
	v_mul_f32_e32 v110, 0x44000000, v110
	v_mul_f32_e32 v97, 0x44000000, v97
	s_waitcnt lgkmcnt(0)
	v_add_f32_e32 v96, v170, v96
	v_cvt_pk_fp8_f32 v109, v110, v97 op_sel:[0,0,1]
	ds_bpermute_b32 v97, v242, v96
	s_mov_b64 s[24:25], 0x4000
	v_lshl_add_u64 v[110:111], v[208:209], 0, s[24:25]
	global_store_dwordx4 v[218:219], v[98:101], off
	global_store_dwordx4 v[218:219], v[102:105], off offset:16
	global_store_dwordx4 v[110:111], v[106:109], off
	s_and_saveexec_b64 s[24:25], s[0:1]
	s_cbranch_execz .LBB0_900
	s_waitcnt lgkmcnt(0)
	v_add_f32_e32 v96, v96, v97
	global_atomic_add_f32 v[148:149], v96, off offset:64
.LBB0_900:
	s_or_b64 exec, exec, s[24:25]
	v_add_co_u32_e32 v96, vcc, 0x50000, v214
	s_mov_b64 s[24:25], 0x50000
	s_waitcnt lgkmcnt(0)
	v_addc_co_u32_e32 v97, vcc, 0, v215, vcc
	v_add_co_u32_e32 v100, vcc, 0x28000, v208
	v_lshl_add_u64 v[108:109], v[214:215], 0, s[24:25]
	s_nop 0
	v_addc_co_u32_e32 v101, vcc, 0, v209, vcc
	global_load_dwordx4 v[104:107], v[96:97], off nt
	s_nop 0
	global_load_dwordx4 v[96:99], v[108:109], off offset:16 nt
	v_cvt_f32_fp8_sdwa v166, v156 src0_sel:BYTE_2
	global_load_dwordx4 v[100:103], v[100:101], off nt
	v_cvt_f32_fp8_sdwa v167, v156 src0_sel:BYTE_3
	v_lshlrev_b32_e32 v110, 16, v160
	v_and_b32_e32 v111, 0xffff0000, v160
	v_cvt_f32_fp8_e32 v164, v156
	v_cvt_f32_fp8_sdwa v165, v156 src0_sel:BYTE_1
	v_lshlrev_b32_e32 v160, 16, v161
	v_and_b32_e32 v161, 0xffff0000, v161
	v_pk_fma_f32 v[160:161], v[166:167], s[76:77], v[160:161] op_sel_hi:[1,0,1]
	v_cvt_f32_fp8_e32 v156, v157
	v_cvt_f32_fp8_sdwa v166, v157 src0_sel:BYTE_2
	v_cvt_f32_fp8_sdwa v167, v157 src0_sel:BYTE_3
	v_cvt_f32_fp8_sdwa v157, v157 src0_sel:BYTE_1
	v_cvt_f32_fp8_sdwa v168, v158 src0_sel:BYTE_2
	v_cvt_f32_fp8_sdwa v169, v158 src0_sel:BYTE_3
	v_pk_fma_f32 v[110:111], v[164:165], s[76:77], v[110:111] op_sel_hi:[1,0,1]
	v_lshlrev_b32_e32 v164, 16, v162
	v_and_b32_e32 v165, 0xffff0000, v162
	v_lshlrev_b32_e32 v162, 16, v163
	v_and_b32_e32 v163, 0xffff0000, v163
	v_pk_fma_f32 v[162:163], v[166:167], s[76:77], v[162:163] op_sel_hi:[1,0,1]
	v_pk_fma_f32 v[156:157], v[156:157], s[76:77], v[164:165] op_sel_hi:[1,0,1]
	v_lshlrev_b32_e32 v164, 16, v152
	v_and_b32_e32 v165, 0xffff0000, v152
	v_cvt_f32_fp8_e32 v166, v158
	v_cvt_f32_fp8_sdwa v167, v158 src0_sel:BYTE_1
	v_lshlrev_b32_e32 v152, 16, v153
	v_and_b32_e32 v153, 0xffff0000, v153
	v_pk_fma_f32 v[152:153], v[168:169], s[76:77], v[152:153] op_sel_hi:[1,0,1]
	v_cvt_f32_fp8_sdwa v168, v159 src0_sel:BYTE_2
	v_cvt_f32_fp8_sdwa v169, v159 src0_sel:BYTE_3
	v_pk_fma_f32 v[164:165], v[166:167], s[76:77], v[164:165] op_sel_hi:[1,0,1]
	v_lshlrev_b32_e32 v166, 16, v154
	v_and_b32_e32 v167, 0xffff0000, v154
	v_lshlrev_b32_e32 v154, 16, v155
	v_and_b32_e32 v155, 0xffff0000, v155
	v_pk_fma_f32 v[154:155], v[168:169], s[76:77], v[154:155] op_sel_hi:[1,0,1]
	v_pk_add_f32 v[92:93], v[92:93], v[110:111]
; __device__ __forceinline__ float bflo(unsigned u) { return __uint_as_float(u << 16); }
; __device__ __forceinline__ float bfhi(unsigned u) { return __uint_as_float(u & 0xffff0000u); }
; __device__ __forceinline__ unsigned pk2(float lo, float hi) { f32x2 v = {lo, hi}; bf2_t b = __builtin_convertvector(v, bf2_t); return __builtin_bit_cast(unsigned, b); }
;     __device__ __forceinline__ void operator()(const AccT& acc, const Unit& u, int wr, int wc, int fr, int fq) const {
;     ...
;             x[0] = (f32x4){bflo(h0.x), bfhi(h0.x), bflo(h0.y), bfhi(h0.y)} + un_lo8(l0.x);
;             x[1] = (f32x4){bflo(h0.z), bfhi(h0.z), bflo(h0.w), bfhi(h0.w)} + un_lo8(l0.y);
;             x[2] = (f32x4){bflo(h1.x), bfhi(h1.x), bflo(h1.y), bfhi(h1.y)} + un_lo8(l0.z);
;             x[3] = (f32x4){bflo(h1.z), bfhi(h1.z), bflo(h1.w), bfhi(h1.w)} + un_lo8(l0.w);
; #pragma unroll
;             for (int q = 0; q < 4; ++q) { x[q] = x[q] + scale * acc[ai][q >> 1][m][q & 1];
;                 s += (x[q][0] * x[q][0] + x[q][1] * x[q][1]) + (x[q][2] * x[q][2] + x[q][3] * x[q][3]); }
;             if (last) { float* p = OUT + off;
; #pragma unroll
;                 for (int q = 0; q < 4; ++q) *(f32x4*)(p + 4 * q) = x[q];
;             } else {
;                 u32x4 w0, w1, v0;
;                 w0.x = pk2(x[0][0], x[0][1]); w0.y = pk2(x[0][2], x[0][3]); w0.z = pk2(x[1][0], x[1][1]); w0.w = pk2(x[1][2], x[1][3]);
;                 w1.x = pk2(x[2][0], x[2][1]); w1.y = pk2(x[2][2], x[2][3]); w1.z = pk2(x[3][0], x[3][1]); w1.w = pk2(x[3][2], x[3][3]);
;                 v0.x = pk_lo8(x[0][0] - bflo(w0.x), x[0][1] - bfhi(w0.x), x[0][2] - bflo(w0.y), x[0][3] - bfhi(w0.y));
;                 v0.y = pk_lo8(x[1][0] - bflo(w0.z), x[1][1] - bfhi(w0.z), x[1][2] - bflo(w0.w), x[1][3] - bfhi(w0.w));
;                 v0.z = pk_lo8(x[2][0] - bflo(w1.x), x[2][1] - bfhi(w1.x), x[2][2] - bflo(w1.y), x[2][3] - bfhi(w1.y));
;                 v0.w = pk_lo8(x[3][0] - bflo(w1.z), x[3][1] - bfhi(w1.z), x[3][2] - bflo(w1.w), x[3][3] - bfhi(w1.w));
;                 u32x4* xb = (u32x4*)(XB + off); xb[0] = w0; xb[1] = w1;
;                 *(u32x4*)(XL + off) = v0;
;                 s += shx(s, LANE_, 16); s += shx(s, LANE_, 32);
;                 if (fq == 0) atomicAdd(ssq_next + row, s);
	v_pk_add_f32 v[94:95], v[94:95], v[160:161]
	v_pk_add_f32 v[154:155], v[82:83], v[154:155]
	v_mul_f32_e32 v82, v93, v93
	v_mul_f32_e32 v83, v95, v95
	v_pk_add_f32 v[110:111], v[88:89], v[156:157]
	v_pk_add_f32 v[156:157], v[90:91], v[162:163]
	v_fmac_f32_e32 v82, v92, v92
	v_fmac_f32_e32 v83, v94, v94
	v_cvt_f32_fp8_e32 v158, v159
	v_cvt_f32_fp8_sdwa v159, v159 src0_sel:BYTE_1
	v_pk_add_f32 v[160:161], v[84:85], v[164:165]
	v_add_f32_e32 v82, v82, v83
	v_mul_f32_e32 v83, v111, v111
	v_mul_f32_e32 v84, v157, v157
	v_fmac_f32_e32 v83, v110, v110
	v_fmac_f32_e32 v84, v156, v156
	v_pk_add_f32 v[152:153], v[86:87], v[152:153]
	v_add_f32_e32 v83, v83, v84
	v_add_f32_e32 v82, v82, v83
	v_mul_f32_e32 v83, v161, v161
	v_mul_f32_e32 v84, v153, v153
	v_pk_fma_f32 v[158:159], v[158:159], s[76:77], v[166:167] op_sel_hi:[1,0,1]
	v_fmac_f32_e32 v83, v160, v160
	v_fmac_f32_e32 v84, v152, v152
	v_pk_add_f32 v[80:81], v[80:81], v[158:159]
	v_add_f32_e32 v83, v83, v84
	v_add_f32_e32 v82, v82, v83
	v_mul_f32_e32 v83, v81, v81
	v_mul_f32_e32 v84, v155, v155
	v_fmac_f32_e32 v83, v80, v80
	v_fmac_f32_e32 v84, v154, v154
	v_add_f32_e32 v83, v83, v84
	v_add_f32_e32 v158, v82, v83
	v_cvt_pk_bf16_f32 v82, v92, v93
	v_cvt_pk_bf16_f32 v83, v94, v95
	v_lshlrev_b32_e32 v90, 16, v82
	v_and_b32_e32 v91, 0xffff0000, v82
	v_sub_f32_e32 v90, v92, v90
	v_sub_f32_e32 v91, v93, v91
	v_lshlrev_b32_e32 v92, 16, v83
	v_sub_f32_e32 v92, v94, v92
	v_mul_f32_e32 v94, 0x44000000, v90
	v_mul_f32_e32 v91, 0x44000000, v91
	v_mov_b32_e32 v90, v189
	v_cvt_pk_fp8_f32 v90, v94, v91
	v_and_b32_e32 v93, 0xffff0000, v83
	v_sub_f32_e32 v91, v95, v93
	v_cvt_pk_bf16_f32 v84, v110, v111
	v_mul_f32_e32 v92, 0x44000000, v92
	v_mul_f32_e32 v91, 0x44000000, v91
	v_cvt_pk_fp8_f32 v90, v92, v91 op_sel:[0,0,1]
	v_lshlrev_b32_e32 v91, 16, v84
	v_and_b32_e32 v92, 0xffff0000, v84
	v_sub_f32_e32 v91, v110, v91
	v_sub_f32_e32 v92, v111, v92
	v_mul_f32_e32 v95, 0x44000000, v91
	v_mul_f32_e32 v92, 0x44000000, v92
	v_mov_b32_e32 v91, v189
	v_cvt_pk_bf16_f32 v85, v156, v157
	v_cvt_pk_fp8_f32 v91, v95, v92
	v_lshlrev_b32_e32 v93, 16, v85
	v_and_b32_e32 v94, 0xffff0000, v85
	v_sub_f32_e32 v93, v156, v93
	v_sub_f32_e32 v92, v157, v94
	v_cvt_pk_bf16_f32 v86, v160, v161
	v_mul_f32_e32 v93, 0x44000000, v93
	v_mul_f32_e32 v92, 0x44000000, v92
	v_cvt_pk_fp8_f32 v91, v93, v92 op_sel:[0,0,1]
	v_lshlrev_b32_e32 v92, 16, v86
	v_and_b32_e32 v93, 0xffff0000, v86
	v_sub_f32_e32 v92, v160, v92
	v_sub_f32_e32 v93, v161, v93
	v_mul_f32_e32 v110, 0x44000000, v92
	v_mul_f32_e32 v93, 0x44000000, v93
	v_mov_b32_e32 v92, v189
	v_cvt_pk_bf16_f32 v87, v152, v153
	v_cvt_pk_fp8_f32 v92, v110, v93
	v_lshlrev_b32_e32 v94, 16, v87
	v_and_b32_e32 v95, 0xffff0000, v87
	v_sub_f32_e32 v94, v152, v94
	v_sub_f32_e32 v93, v153, v95
	v_cvt_pk_bf16_f32 v88, v80, v81
	v_mul_f32_e32 v94, 0x44000000, v94
	v_mul_f32_e32 v93, 0x44000000, v93
	v_cvt_pk_fp8_f32 v92, v94, v93 op_sel:[0,0,1]
	v_lshlrev_b32_e32 v93, 16, v88
	v_cvt_pk_bf16_f32 v89, v154, v155
	v_sub_f32_e32 v80, v80, v93
	v_and_b32_e32 v93, 0xffff0000, v88
	v_sub_f32_e32 v81, v81, v93
	v_lshlrev_b32_e32 v93, 16, v89
	v_sub_f32_e32 v94, v154, v93
	v_mul_f32_e32 v80, 0x44000000, v80
	v_mul_f32_e32 v81, 0x44000000, v81
	v_mov_b32_e32 v93, v189
	v_cvt_pk_fp8_f32 v93, v80, v81
	ds_bpermute_b32 v80, v241, v158
	v_and_b32_e32 v95, 0xffff0000, v89
	v_sub_f32_e32 v81, v155, v95
	v_mul_f32_e32 v94, 0x44000000, v94
	v_mul_f32_e32 v81, 0x44000000, v81
	s_waitcnt lgkmcnt(0)
	v_add_f32_e32 v80, v158, v80
	v_cvt_pk_fp8_f32 v93, v94, v81 op_sel:[0,0,1]
	ds_bpermute_b32 v81, v242, v80
	s_mov_b64 s[24:25], 0x8000
	v_lshl_add_u64 v[94:95], v[208:209], 0, s[24:25]
	global_store_dwordx4 v[216:217], v[82:85], off
	global_store_dwordx4 v[216:217], v[86:89], off offset:16
	global_store_dwordx4 v[94:95], v[90:93], off
	s_and_saveexec_b64 s[24:25], s[0:1]
	s_cbranch_execz .LBB0_902
	s_waitcnt lgkmcnt(0)
	v_add_f32_e32 v80, v80, v81
	global_atomic_add_f32 v[148:149], v80, off offset:128
; __device__ __forceinline__ float bflo(unsigned u) { return __uint_as_float(u << 16); }
; __device__ __forceinline__ float bfhi(unsigned u) { return __uint_as_float(u & 0xffff0000u); }
;     __device__ __forceinline__ void operator()(const AccT& acc, const Unit& u, int wr, int wc, int fr, int fq) const {
;     ...
;             if (idx + 4 < 8) { const size_t o = off0 + (size_t)(128 + (idx & 3) * 16) * DM;
;                 hr[idx & 3][0] = *(const u32x4*)(XB + o); hr[idx & 3][1] = *(const u32x4*)(XB + o + 8); lr[idx & 3] = *(const u32x4*)(XL + o); }
;             f32x4 x[4];
;             x[0] = (f32x4){bflo(h0.x), bfhi(h0.x), bflo(h0.y), bfhi(h0.y)} + un_lo8(l0.x);
;             x[1] = (f32x4){bflo(h0.z), bfhi(h0.z), bflo(h0.w), bfhi(h0.w)} + un_lo8(l0.y);
;             x[2] = (f32x4){bflo(h1.x), bfhi(h1.x), bflo(h1.y), bfhi(h1.y)} + un_lo8(l0.z);
;             x[3] = (f32x4){bflo(h1.z), bfhi(h1.z), bflo(h1.w), bfhi(h1.w)} + un_lo8(l0.w);
; #pragma unroll
;             for (int q = 0; q < 4; ++q) { x[q] = x[q] + scale * acc[ai][q >> 1][m][q & 1];
;                 s += (x[q][0] * x[q][0] + x[q][1] * x[q][1]) + (x[q][2] * x[q][2] + x[q][3] * x[q][3]); }
;             if (last) { float* p = OUT + off;
; #pragma unroll
;                 for (int q = 0; q < 4; ++q) *(f32x4*)(p + 4 * q) = x[q];
;             } else {
;                 u32x4 w0, w1, v0;
;                 w0.x = pk2(x[0][0], x[0][1]); w0.y = pk2(x[0][2], x[0][3]); w0.z = pk2(x[1][0], x[1][1]); w0.w = pk2(x[1][2], x[1][3]);
;                 w1.x = pk2(x[2][0], x[2][1]); w1.y = pk2(x[2][2], x[2][3]); w1.z = pk2(x[3][0], x[3][1]); w1.w = pk2(x[3][2], x[3][3]);
;                 v0.x = pk_lo8(x[0][0] - bflo(w0.x), x[0][1] - bfhi(w0.x), x[0][2] - bflo(w0.y), x[0][3] - bfhi(w0.y));
;                 v0.y = pk_lo8(x[1][0] - bflo(w0.z), x[1][1] - bfhi(w0.z), x[1][2] - bflo(w0.w), x[1][3] - bfhi(w0.w));
;                 v0.z = pk_lo8(x[2][0] - bflo(w1.x), x[2][1] - bfhi(w1.x), x[2][2] - bflo(w1.y), x[2][3] - bfhi(w1.y));
;                 v0.w = pk_lo8(x[3][0] - bflo(w1.z), x[3][1] - bfhi(w1.z), x[3][2] - bflo(w1.w), x[3][3] - bfhi(w1.w));
;                 u32x4* xb = (u32x4*)(XB + off); xb[0] = w0; xb[1] = w1;
;                 *(u32x4*)(XL + off) = v0;
;                 s += shx(s, LANE_, 16); s += shx(s, LANE_, 32);
;                 if (fq == 0) atomicAdd(ssq_next + row, s);
.LBB0_902:
	s_or_b64 exec, exec, s[24:25]
	v_add_co_u32_e32 v80, vcc, 0x58000, v214
	v_lshl_add_u64 v[92:93], v[214:215], 0, s[90:91]
	s_waitcnt lgkmcnt(0)
	v_addc_co_u32_e32 v81, vcc, 0, v215, vcc
	v_add_co_u32_e32 v84, vcc, 0x2c000, v208
	global_load_dwordx4 v[88:91], v[80:81], off nt
	s_nop 0
	global_load_dwordx4 v[80:83], v[92:93], off offset:16 nt
	v_addc_co_u32_e32 v85, vcc, 0, v209, vcc
	global_load_dwordx4 v[84:87], v[84:85], off nt
	v_cvt_f32_fp8_sdwa v152, v128 src0_sel:BYTE_2
	v_cvt_f32_fp8_sdwa v153, v128 src0_sel:BYTE_3
	v_lshlrev_b32_e32 v94, 16, v140
	v_and_b32_e32 v95, 0xffff0000, v140
	v_cvt_f32_fp8_e32 v110, v128
	v_cvt_f32_fp8_sdwa v111, v128 src0_sel:BYTE_1
	v_lshlrev_b32_e32 v140, 16, v141
	v_and_b32_e32 v141, 0xffff0000, v141
	v_pk_fma_f32 v[140:141], v[152:153], s[76:77], v[140:141] op_sel_hi:[1,0,1]
	v_cvt_f32_fp8_e32 v128, v129
	v_cvt_f32_fp8_sdwa v152, v129 src0_sel:BYTE_2
	v_cvt_f32_fp8_sdwa v153, v129 src0_sel:BYTE_3
	v_cvt_f32_fp8_sdwa v129, v129 src0_sel:BYTE_1
	v_cvt_f32_fp8_sdwa v154, v130 src0_sel:BYTE_2
	v_cvt_f32_fp8_sdwa v155, v130 src0_sel:BYTE_3
	v_pk_fma_f32 v[94:95], v[110:111], s[76:77], v[94:95] op_sel_hi:[1,0,1]
	v_lshlrev_b32_e32 v110, 16, v142
	v_and_b32_e32 v111, 0xffff0000, v142
	v_lshlrev_b32_e32 v142, 16, v143
	v_and_b32_e32 v143, 0xffff0000, v143
	v_pk_fma_f32 v[142:143], v[152:153], s[76:77], v[142:143] op_sel_hi:[1,0,1]
	v_pk_fma_f32 v[110:111], v[128:129], s[76:77], v[110:111] op_sel_hi:[1,0,1]
	v_lshlrev_b32_e32 v128, 16, v124
	v_and_b32_e32 v129, 0xffff0000, v124
	v_cvt_f32_fp8_e32 v152, v130
	v_cvt_f32_fp8_sdwa v153, v130 src0_sel:BYTE_1
	v_lshlrev_b32_e32 v124, 16, v125
	v_and_b32_e32 v125, 0xffff0000, v125
	v_pk_fma_f32 v[124:125], v[154:155], s[76:77], v[124:125] op_sel_hi:[1,0,1]
	v_cvt_f32_fp8_sdwa v154, v131 src0_sel:BYTE_2
	v_cvt_f32_fp8_sdwa v155, v131 src0_sel:BYTE_3
	v_pk_fma_f32 v[128:129], v[152:153], s[76:77], v[128:129] op_sel_hi:[1,0,1]
	v_lshlrev_b32_e32 v152, 16, v126
	v_and_b32_e32 v153, 0xffff0000, v126
	v_lshlrev_b32_e32 v126, 16, v127
	v_and_b32_e32 v127, 0xffff0000, v127
	v_pk_fma_f32 v[126:127], v[154:155], s[76:77], v[126:127] op_sel_hi:[1,0,1]
	v_pk_add_f32 v[76:77], v[76:77], v[94:95]
	v_pk_add_f32 v[78:79], v[78:79], v[140:141]
	v_pk_add_f32 v[126:127], v[66:67], v[126:127]
	v_mul_f32_e32 v66, v77, v77
	v_mul_f32_e32 v67, v79, v79
	v_pk_add_f32 v[94:95], v[72:73], v[110:111]
	v_pk_add_f32 v[110:111], v[74:75], v[142:143]
	v_fmac_f32_e32 v66, v76, v76
	v_fmac_f32_e32 v67, v78, v78
	v_cvt_f32_fp8_e32 v130, v131
	v_cvt_f32_fp8_sdwa v131, v131 src0_sel:BYTE_1
	v_pk_add_f32 v[128:129], v[68:69], v[128:129]
	v_add_f32_e32 v66, v66, v67
	v_mul_f32_e32 v67, v95, v95
	v_mul_f32_e32 v68, v111, v111
	v_fmac_f32_e32 v67, v94, v94
	v_fmac_f32_e32 v68, v110, v110
	v_pk_add_f32 v[124:125], v[70:71], v[124:125]
	v_add_f32_e32 v67, v67, v68
	v_add_f32_e32 v66, v66, v67
	v_mul_f32_e32 v67, v129, v129
	v_mul_f32_e32 v68, v125, v125
	v_pk_fma_f32 v[130:131], v[130:131], s[76:77], v[152:153] op_sel_hi:[1,0,1]
	v_fmac_f32_e32 v67, v128, v128
	v_fmac_f32_e32 v68, v124, v124
	v_pk_add_f32 v[64:65], v[64:65], v[130:131]
	v_add_f32_e32 v67, v67, v68
	v_add_f32_e32 v66, v66, v67
	v_mul_f32_e32 v67, v65, v65
	v_mul_f32_e32 v68, v127, v127
	v_fmac_f32_e32 v67, v64, v64
	v_fmac_f32_e32 v68, v126, v126
	v_add_f32_e32 v67, v67, v68
	v_add_f32_e32 v130, v66, v67
	v_cvt_pk_bf16_f32 v66, v76, v77
	v_cvt_pk_bf16_f32 v67, v78, v79
	v_lshlrev_b32_e32 v74, 16, v66
	v_and_b32_e32 v75, 0xffff0000, v66
	v_sub_f32_e32 v74, v76, v74
	v_sub_f32_e32 v75, v77, v75
	v_lshlrev_b32_e32 v76, 16, v67
	v_sub_f32_e32 v76, v78, v76
	v_mul_f32_e32 v78, 0x44000000, v74
	v_mul_f32_e32 v75, 0x44000000, v75
	v_mov_b32_e32 v74, v189
	v_cvt_pk_fp8_f32 v74, v78, v75
	v_and_b32_e32 v77, 0xffff0000, v67
	v_sub_f32_e32 v75, v79, v77
	v_cvt_pk_bf16_f32 v68, v94, v95
	v_mul_f32_e32 v76, 0x44000000, v76
	v_mul_f32_e32 v75, 0x44000000, v75
	v_cvt_pk_fp8_f32 v74, v76, v75 op_sel:[0,0,1]
	v_lshlrev_b32_e32 v75, 16, v68
	v_and_b32_e32 v76, 0xffff0000, v68
	v_sub_f32_e32 v75, v94, v75
	v_sub_f32_e32 v76, v95, v76
	v_mul_f32_e32 v79, 0x44000000, v75
	v_mul_f32_e32 v76, 0x44000000, v76
	v_mov_b32_e32 v75, v189
	v_cvt_pk_bf16_f32 v69, v110, v111
	v_cvt_pk_fp8_f32 v75, v79, v76
	v_lshlrev_b32_e32 v77, 16, v69
	v_and_b32_e32 v78, 0xffff0000, v69
	v_sub_f32_e32 v77, v110, v77
	v_sub_f32_e32 v76, v111, v78
	v_cvt_pk_bf16_f32 v70, v128, v129
	v_mul_f32_e32 v77, 0x44000000, v77
	v_mul_f32_e32 v76, 0x44000000, v76
	v_cvt_pk_fp8_f32 v75, v77, v76 op_sel:[0,0,1]
	v_lshlrev_b32_e32 v76, 16, v70
	v_and_b32_e32 v77, 0xffff0000, v70
	v_sub_f32_e32 v76, v128, v76
	v_sub_f32_e32 v77, v129, v77
	v_mul_f32_e32 v94, 0x44000000, v76
	v_mul_f32_e32 v77, 0x44000000, v77
	v_mov_b32_e32 v76, v189
	v_cvt_pk_bf16_f32 v71, v124, v125
	v_cvt_pk_fp8_f32 v76, v94, v77
	v_lshlrev_b32_e32 v78, 16, v71
	v_and_b32_e32 v79, 0xffff0000, v71
	v_sub_f32_e32 v78, v124, v78
	v_sub_f32_e32 v77, v125, v79
	v_cvt_pk_bf16_f32 v72, v64, v65
	v_mul_f32_e32 v78, 0x44000000, v78
	v_mul_f32_e32 v77, 0x44000000, v77
	v_cvt_pk_fp8_f32 v76, v78, v77 op_sel:[0,0,1]
	v_lshlrev_b32_e32 v77, 16, v72
	v_cvt_pk_bf16_f32 v73, v126, v127
	v_sub_f32_e32 v64, v64, v77
	v_and_b32_e32 v77, 0xffff0000, v72
	v_sub_f32_e32 v65, v65, v77
	v_lshlrev_b32_e32 v77, 16, v73
	v_sub_f32_e32 v78, v126, v77
	v_mul_f32_e32 v64, 0x44000000, v64
	v_mul_f32_e32 v65, 0x44000000, v65
	v_mov_b32_e32 v77, v189
	v_cvt_pk_fp8_f32 v77, v64, v65
	ds_bpermute_b32 v64, v241, v130
	v_and_b32_e32 v79, 0xffff0000, v73
	v_sub_f32_e32 v65, v127, v79
	v_mul_f32_e32 v78, 0x44000000, v78
	v_mul_f32_e32 v65, 0x44000000, v65
	s_waitcnt lgkmcnt(0)
	v_add_f32_e32 v64, v130, v64
	v_cvt_pk_fp8_f32 v77, v78, v65 op_sel:[0,0,1]
	ds_bpermute_b32 v65, v242, v64
	s_mov_b64 s[24:25], 0xc000
	v_lshl_add_u64 v[78:79], v[208:209], 0, s[24:25]
	global_store_dwordx4 v[212:213], v[66:69], off
	global_store_dwordx4 v[212:213], v[70:73], off offset:16
	global_store_dwordx4 v[78:79], v[74:77], off
	s_and_saveexec_b64 s[24:25], s[0:1]
	s_cbranch_execz .LBB0_904
	s_waitcnt lgkmcnt(0)
	v_add_f32_e32 v64, v64, v65
	global_atomic_add_f32 v[148:149], v64, off offset:192

; __device__ __forceinline__ float bflo(unsigned u) { return __uint_as_float(u << 16); }
; __device__ __forceinline__ float bfhi(unsigned u) { return __uint_as_float(u & 0xffff0000u); }
; #define EPI_SCHED() do {} while (0)
; __device__ __forceinline__ f32x4 un_lo8(unsigned w) { return (f32x4){__builtin_amdgcn_cvt_f32_fp8((int)w, 0), __builtin_amdgcn_cvt_f32_fp8((int)w, 1), __builtin_amdgcn_cvt_f32_fp8((int)w, 2), __builtin_amdgcn_cvt_f32_fp8((int)w, 3)} * (1.f / 512.f); }
;     __device__ __forceinline__ void operator()(const AccT& acc, const Unit& u, int wr, int wc, int fr, int fq) const {
;         const int row0 = u.pm * 256 + wr * 64 + fr, col0 = u.pn * 256 + wc * 64 + 16 * fq;
;         const size_t off0 = (size_t)row0 * DM + col0;
;         u32x4 hr[4][2], lr[4];
; #pragma unroll
;         for (int i = 0; i < 4; ++i) { const size_t o = off0 + (size_t)(i * 16) * DM; hr[i][0] = *(const u32x4*)(XB + o); hr[i][1] = *(const u32x4*)(XB + o + 8); lr[i] = *(const u32x4*)(XL + o); }
;         EPI_SCHED();
; #pragma unroll
;         for (int idx = 0; idx < 8; ++idx) {
;             const int ai = idx >> 2, m = idx & 3, rofs = ai * 128 + m * 16;
;             const int row = row0 + rofs; float s = 0.f;
;             const size_t off = off0 + (size_t)rofs * DM;
;             const u32x4 h0 = hr[idx & 3][0], h1 = hr[idx & 3][1], l0 = lr[idx & 3];
;             if (idx + 4 < 8) { const size_t o = off0 + (size_t)(128 + (idx & 3) * 16) * DM;
;                 hr[idx & 3][0] = *(const u32x4*)(XB + o); hr[idx & 3][1] = *(const u32x4*)(XB + o + 8); lr[idx & 3] = *(const u32x4*)(XL + o); }
;             f32x4 x[4];
;             x[0] = (f32x4){bflo(h0.x), bfhi(h0.x), bflo(h0.y), bfhi(h0.y)} + un_lo8(l0.x);
;             x[1] = (f32x4){bflo(h0.z), bfhi(h0.z), bflo(h0.w), bfhi(h0.w)} + un_lo8(l0.y);
;             x[2] = (f32x4){bflo(h1.x), bfhi(h1.x), bflo(h1.y), bfhi(h1.y)} + un_lo8(l0.z);
;             x[3] = (f32x4){bflo(h1.z), bfhi(h1.z), bflo(h1.w), bfhi(h1.w)} + un_lo8(l0.w);
; #pragma unroll
;             for (int q = 0; q < 4; ++q) { x[q] = x[q] + scale * acc[ai][q >> 1][m][q & 1];
;                 s += (x[q][0] * x[q][0] + x[q][1] * x[q][1]) + (x[q][2] * x[q][2] + x[q][3] * x[q][3]); }
;             if (last) { float* p = OUT + off;
.LBB0_1058:
	v_lshl_add_u32 v186, s44, 8, v212
	v_lshl_or_b32 v96, s43, 8, v216
	v_ashrrev_i32_e32 v187, 31, v186
	v_lshlrev_b64 v[98:99], 10, v[186:187]
	v_ashrrev_i32_e32 v97, 31, v96
	v_lshl_add_u64 v[200:201], v[98:99], 0, v[96:97]
	v_lshl_add_u64 v[206:207], v[200:201], 1, s[12:13]
	v_lshl_add_u64 v[198:199], s[10:11], 0, v[200:201]
	s_mov_b64 s[4:5], 0x8000
	v_add_co_u32_e32 v96, vcc, s85, v206
	global_load_dwordx4 v[218:221], v[206:207], off offset:16 nt
	global_load_dwordx4 v[228:231], v[206:207], off nt
	global_load_dwordx4 v[232:235], v[198:199], off nt
	v_lshl_add_u64 v[210:211], v[206:207], 0, s[4:5]
	v_addc_co_u32_e32 v97, vcc, 0, v207, vcc
	s_movk_i32 s4, 0x4000
	global_load_dwordx4 v[172:175], v[96:97], off nt
	global_load_dwordx4 v[164:167], v[210:211], off offset:16 nt
	v_add_co_u32_e32 v96, vcc, s4, v198
	v_lshl_add_u64 v[208:209], v[206:207], 0, s[56:57]
	s_nop 0
	v_addc_co_u32_e32 v97, vcc, 0, v199, vcc
	global_load_dwordx4 v[168:171], v[96:97], off nt
	v_add_co_u32_e32 v96, vcc, s84, v206
	s_mov_b64 s[4:5], 0x18000
	s_nop 0
	v_addc_co_u32_e32 v97, vcc, 0, v207, vcc
	global_load_dwordx4 v[160:163], v[96:97], off nt
	global_load_dwordx4 v[152:155], v[208:209], off offset:16 nt
	v_add_co_u32_e32 v96, vcc, s85, v198
	v_lshl_add_u64 v[204:205], v[206:207], 0, s[4:5]
	s_nop 0
	v_addc_co_u32_e32 v97, vcc, 0, v199, vcc
	global_load_dwordx4 v[156:159], v[96:97], off nt
	v_add_co_u32_e32 v96, vcc, s83, v206
	s_mov_b32 s4, 0xc000
	s_nop 0
	v_addc_co_u32_e32 v97, vcc, 0, v207, vcc
	global_load_dwordx4 v[144:147], v[96:97], off nt
	global_load_dwordx4 v[136:139], v[204:205], off offset:16 nt
	v_add_co_u32_e32 v96, vcc, s4, v198
	s_mov_b64 s[4:5], 0x40000
	s_nop 0
	v_addc_co_u32_e32 v97, vcc, 0, v199, vcc
	global_load_dwordx4 v[140:143], v[96:97], off nt
	v_add_co_u32_e32 v96, vcc, s82, v206
	v_lshl_add_u64 v[202:203], v[206:207], 0, s[4:5]
	s_nop 0
	v_addc_co_u32_e32 v97, vcc, 0, v207, vcc
	s_mov_b32 s4, 0x20000
	v_add_co_u32_e32 v100, vcc, s4, v198
	global_load_dwordx4 v[104:107], v[96:97], off nt
	s_nop 0
	global_load_dwordx4 v[96:99], v[202:203], off offset:16 nt
	v_addc_co_u32_e32 v101, vcc, 0, v199, vcc
	global_load_dwordx4 v[100:103], v[100:101], off nt
	v_readlane_b32 s22, v253, 36
	v_readlane_b32 s23, v253, 37
	s_mov_b64 s[4:5], -1
	s_and_b64 vcc, exec, s[22:23]
	s_mov_b64 s[26:27], 0x80000
	s_waitcnt vmcnt(0)
	v_lshlrev_b32_e32 v222, 16, v228
	v_cvt_f32_fp8_sdwa v242, v232 src0_sel:BYTE_2
	v_cvt_f32_fp8_sdwa v243, v232 src0_sel:BYTE_3
	v_and_b32_e32 v223, 0xffff0000, v228
	v_lshlrev_b32_e32 v228, 16, v229
	v_and_b32_e32 v229, 0xffff0000, v229
	v_cvt_f32_fp8_e32 v240, v232
	v_cvt_f32_fp8_sdwa v241, v232 src0_sel:BYTE_1
	v_pk_fma_f32 v[228:229], v[242:243], s[76:77], v[228:229] op_sel_hi:[1,0,1]
	v_cvt_f32_fp8_e32 v242, v233
	v_cvt_f32_fp8_sdwa v243, v233 src0_sel:BYTE_1
	v_cvt_f32_fp8_sdwa v232, v233 src0_sel:BYTE_2
	v_cvt_f32_fp8_sdwa v233, v233 src0_sel:BYTE_3
	v_cvt_f32_fp8_sdwa v244, v234 src0_sel:BYTE_2
	v_cvt_f32_fp8_sdwa v245, v234 src0_sel:BYTE_3
	v_pk_fma_f32 v[222:223], v[240:241], s[76:77], v[222:223] op_sel_hi:[1,0,1]
	v_lshlrev_b32_e32 v240, 16, v230
	v_and_b32_e32 v241, 0xffff0000, v230
	v_lshlrev_b32_e32 v230, 16, v231
	v_and_b32_e32 v231, 0xffff0000, v231
	v_pk_fma_f32 v[240:241], v[242:243], s[76:77], v[240:241] op_sel_hi:[1,0,1]
	v_pk_fma_f32 v[230:231], v[232:233], s[76:77], v[230:231] op_sel_hi:[1,0,1]
	v_lshlrev_b32_e32 v232, 16, v218
	v_and_b32_e32 v233, 0xffff0000, v218
	v_lshlrev_b32_e32 v218, 16, v219
	v_and_b32_e32 v219, 0xffff0000, v219
	v_cvt_f32_fp8_e32 v242, v234
	v_cvt_f32_fp8_sdwa v243, v234 src0_sel:BYTE_1
	v_pk_fma_f32 v[218:219], v[244:245], s[76:77], v[218:219] op_sel_hi:[1,0,1]
	v_cvt_f32_fp8_e32 v244, v235
	v_cvt_f32_fp8_sdwa v245, v235 src0_sel:BYTE_1
	v_cvt_f32_fp8_sdwa v234, v235 src0_sel:BYTE_2
	v_cvt_f32_fp8_sdwa v235, v235 src0_sel:BYTE_3
	v_pk_fma_f32 v[232:233], v[242:243], s[76:77], v[232:233] op_sel_hi:[1,0,1]
	v_lshlrev_b32_e32 v242, 16, v220
	v_and_b32_e32 v243, 0xffff0000, v220
	v_lshlrev_b32_e32 v220, 16, v221
	v_and_b32_e32 v221, 0xffff0000, v221
	v_pk_fma_f32 v[242:243], v[244:245], s[76:77], v[242:243] op_sel_hi:[1,0,1]
	v_pk_fma_f32 v[220:221], v[234:235], s[76:77], v[220:221] op_sel_hi:[1,0,1]
	v_pk_fma_f32 v[150:151], v[150:151], 0.5, v[228:229] op_sel_hi:[1,0,1]
	v_pk_fma_f32 v[148:149], v[148:149], 0.5, v[222:223] op_sel_hi:[1,0,1]
	v_pk_fma_f32 v[126:127], v[126:127], 0.5, v[230:231] op_sel_hi:[1,0,1]
	v_pk_fma_f32 v[124:125], v[124:125], 0.5, v[240:241] op_sel_hi:[1,0,1]
	v_pk_fma_f32 v[118:119], v[118:119], 0.5, v[218:219] op_sel_hi:[1,0,1]
	v_pk_fma_f32 v[116:117], v[116:117], 0.5, v[232:233] op_sel_hi:[1,0,1]
	v_pk_fma_f32 v[110:111], v[110:111], 0.5, v[220:221] op_sel_hi:[1,0,1]
	v_pk_fma_f32 v[108:109], v[108:109], 0.5, v[242:243] op_sel_hi:[1,0,1]
	s_cbranch_vccz .LBB0_1062
; __device__ __forceinline__ float bflo(unsigned u) { return __uint_as_float(u << 16); }
; __device__ __forceinline__ float bfhi(unsigned u) { return __uint_as_float(u & 0xffff0000u); }
; __device__ __forceinline__ unsigned pk2(float lo, float hi) { f32x2 v = {lo, hi}; bf2_t b = __builtin_convertvector(v, bf2_t); return __builtin_bit_cast(unsigned, b); }
; __device__ __forceinline__ float shx(float v, int lane, int mask) { return __int_as_float(__builtin_amdgcn_ds_bpermute((lane ^ mask) << 2, __float_as_int(v))); }
; __device__ __forceinline__ unsigned pk_lo8(float a, float b, float c, float d) { int w = 0; w = __builtin_amdgcn_cvt_pk_fp8_f32(a * 512.f, b * 512.f, w, false); w = __builtin_amdgcn_cvt_pk_fp8_f32(c * 512.f, d * 512.f, w, true); return (unsigned)w; }
;     __device__ __forceinline__ void operator()(const AccT& acc, const Unit& u, int wr, int wc, int fr, int fq) const {
;     ...
;                 u32x4 w0, w1, v0;
;                 w0.x = pk2(x[0][0], x[0][1]); w0.y = pk2(x[0][2], x[0][3]); w0.z = pk2(x[1][0], x[1][1]); w0.w = pk2(x[1][2], x[1][3]);
;                 w1.x = pk2(x[2][0], x[2][1]); w1.y = pk2(x[2][2], x[2][3]); w1.z = pk2(x[3][0], x[3][1]); w1.w = pk2(x[3][2], x[3][3]);
;                 v0.x = pk_lo8(x[0][0] - bflo(w0.x), x[0][1] - bfhi(w0.x), x[0][2] - bflo(w0.y), x[0][3] - bfhi(w0.y));
;                 v0.y = pk_lo8(x[1][0] - bflo(w0.z), x[1][1] - bfhi(w0.z), x[1][2] - bflo(w0.w), x[1][3] - bfhi(w0.w));
;                 v0.z = pk_lo8(x[2][0] - bflo(w1.x), x[2][1] - bfhi(w1.x), x[2][2] - bflo(w1.y), x[2][3] - bfhi(w1.y));
;                 v0.w = pk_lo8(x[3][0] - bflo(w1.z), x[3][1] - bfhi(w1.z), x[3][2] - bflo(w1.w), x[3][3] - bfhi(w1.w));
;                 u32x4* xb = (u32x4*)(XB + off); xb[0] = w0; xb[1] = w1;
;                 *(u32x4*)(XL + off) = v0;
;                 s += shx(s, LANE_, 16); s += shx(s, LANE_, 32);
;                 if (fq == 0) atomicAdd(ssq_next + row, s);
	v_mul_f32_e32 v218, v149, v149
	v_mul_f32_e32 v219, v151, v151
	v_fmac_f32_e32 v218, v148, v148
	v_fmac_f32_e32 v219, v150, v150
	v_add_f32_e32 v218, v218, v219
	v_mul_f32_e32 v219, v125, v125
	v_mul_f32_e32 v220, v127, v127
	v_fmac_f32_e32 v219, v124, v124
	v_fmac_f32_e32 v220, v126, v126
	v_add_f32_e32 v219, v219, v220
	v_add_f32_e32 v218, v218, v219
	v_mul_f32_e32 v219, v117, v117
	v_mul_f32_e32 v220, v119, v119
	v_fmac_f32_e32 v219, v116, v116
	v_fmac_f32_e32 v220, v118, v118
	v_add_f32_e32 v219, v219, v220
	v_add_f32_e32 v218, v218, v219
	v_mul_f32_e32 v219, v109, v109
	v_mul_f32_e32 v220, v111, v111
	v_fmac_f32_e32 v219, v108, v108
	v_fmac_f32_e32 v220, v110, v110
	v_add_f32_e32 v219, v219, v220
	v_cvt_pk_bf16_f32 v220, v148, v149
	v_add_f32_e32 v218, v218, v219
	v_cvt_pk_bf16_f32 v221, v150, v151
	v_lshlrev_b32_e32 v219, 16, v220
	v_and_b32_e32 v224, 0xffff0000, v220
	v_sub_f32_e32 v219, v148, v219
	v_sub_f32_e32 v224, v149, v224
	v_lshlrev_b32_e32 v232, 16, v221
	v_sub_f32_e32 v233, v150, v232
	v_mul_f32_e32 v219, 0x44000000, v219
	v_mul_f32_e32 v224, 0x44000000, v224
	v_mov_b32_e32 v232, v189
	v_cvt_pk_fp8_f32 v232, v219, v224
	v_and_b32_e32 v234, 0xffff0000, v221
	v_sub_f32_e32 v219, v151, v234
	v_cvt_pk_bf16_f32 v222, v124, v125
	v_mul_f32_e32 v224, 0x44000000, v233
	v_mul_f32_e32 v219, 0x44000000, v219
	v_cvt_pk_bf16_f32 v223, v126, v127
	v_cvt_pk_fp8_f32 v232, v224, v219 op_sel:[0,0,1]
	v_lshlrev_b32_e32 v219, 16, v222
	v_and_b32_e32 v224, 0xffff0000, v222
	v_sub_f32_e32 v219, v124, v219
	v_sub_f32_e32 v224, v125, v224
	v_lshlrev_b32_e32 v233, 16, v223
	v_sub_f32_e32 v234, v126, v233
	v_mul_f32_e32 v219, 0x44000000, v219
	v_mul_f32_e32 v224, 0x44000000, v224
	v_mov_b32_e32 v233, v189
	v_cvt_pk_fp8_f32 v233, v219, v224
	v_and_b32_e32 v235, 0xffff0000, v223
	v_sub_f32_e32 v219, v127, v235
	v_cvt_pk_bf16_f32 v228, v116, v117
	v_mul_f32_e32 v224, 0x44000000, v234
	v_mul_f32_e32 v219, 0x44000000, v219
	v_cvt_pk_bf16_f32 v229, v118, v119
	v_cvt_pk_fp8_f32 v233, v224, v219 op_sel:[0,0,1]
	v_lshlrev_b32_e32 v219, 16, v228
	v_and_b32_e32 v224, 0xffff0000, v228
	v_sub_f32_e32 v219, v116, v219
	v_sub_f32_e32 v224, v117, v224
	v_lshlrev_b32_e32 v234, 16, v229
	v_sub_f32_e32 v235, v118, v234
	v_mul_f32_e32 v219, 0x44000000, v219
	v_mul_f32_e32 v224, 0x44000000, v224
	v_mov_b32_e32 v234, v189
	v_cvt_pk_fp8_f32 v234, v219, v224
	v_and_b32_e32 v236, 0xffff0000, v229
	v_sub_f32_e32 v219, v119, v236
	v_cvt_pk_bf16_f32 v230, v108, v109
	v_mul_f32_e32 v224, 0x44000000, v235
	v_mul_f32_e32 v219, 0x44000000, v219
	v_cvt_pk_bf16_f32 v231, v110, v111
	v_cvt_pk_fp8_f32 v234, v224, v219 op_sel:[0,0,1]
	v_lshlrev_b32_e32 v219, 16, v230
	v_and_b32_e32 v224, 0xffff0000, v230
	v_sub_f32_e32 v219, v108, v219
	v_sub_f32_e32 v224, v109, v224
	v_lshlrev_b32_e32 v235, 16, v231
	v_sub_f32_e32 v236, v110, v235
	v_mul_f32_e32 v219, 0x44000000, v219
	v_mul_f32_e32 v224, 0x44000000, v224
	v_mov_b32_e32 v235, v189
	v_cvt_pk_fp8_f32 v235, v219, v224
	ds_bpermute_b32 v219, v214, v218
	v_and_b32_e32 v239, 0xffff0000, v231
	v_sub_f32_e32 v224, v111, v239
	v_mul_f32_e32 v236, 0x44000000, v236
	v_mul_f32_e32 v224, 0x44000000, v224
	s_waitcnt lgkmcnt(0)
	v_add_f32_e32 v218, v218, v219
	ds_bpermute_b32 v219, v215, v218
	v_cvt_pk_fp8_f32 v235, v236, v224 op_sel:[0,0,1]
	global_store_dwordx4 v[206:207], v[220:223], off
	global_store_dwordx4 v[206:207], v[228:231], off offset:16
	global_store_dwordx4 v[198:199], v[232:235], off
	s_and_saveexec_b64 s[4:5], s[0:1]
	s_cbranch_execz .LBB0_1061
	v_lshl_add_u64 v[220:221], v[186:187], 2, s[14:15]
	s_waitcnt lgkmcnt(0)
	v_add_f32_e32 v218, v218, v219
	global_atomic_add_f32 v[220:221], v218, off

; __device__ __forceinline__ float bflo(unsigned u) { return __uint_as_float(u << 16); }
; __device__ __forceinline__ float bfhi(unsigned u) { return __uint_as_float(u & 0xffff0000u); }
;     __device__ __forceinline__ void operator()(const AccT& acc, const Unit& u, int wr, int wc, int fr, int fq) const {
;     ...
;             if (idx + 4 < 8) { const size_t o = off0 + (size_t)(128 + (idx & 3) * 16) * DM;
;                 hr[idx & 3][0] = *(const u32x4*)(XB + o); hr[idx & 3][1] = *(const u32x4*)(XB + o + 8); lr[idx & 3] = *(const u32x4*)(XL + o); }
;             f32x4 x[4];
;             x[0] = (f32x4){bflo(h0.x), bfhi(h0.x), bflo(h0.y), bfhi(h0.y)} + un_lo8(l0.x);
;             x[1] = (f32x4){bflo(h0.z), bfhi(h0.z), bflo(h0.w), bfhi(h0.w)} + un_lo8(l0.y);
;             x[2] = (f32x4){bflo(h1.x), bfhi(h1.x), bflo(h1.y), bfhi(h1.y)} + un_lo8(l0.z);
;             x[3] = (f32x4){bflo(h1.z), bfhi(h1.z), bflo(h1.w), bfhi(h1.w)} + un_lo8(l0.w);
; #pragma unroll
;             for (int q = 0; q < 4; ++q) { x[q] = x[q] + scale * acc[ai][q >> 1][m][q & 1];
;                 s += (x[q][0] * x[q][0] + x[q][1] * x[q][1]) + (x[q][2] * x[q][2] + x[q][3] * x[q][3]); }
;             if (last) { float* p = OUT + off;
; #pragma unroll
;                 for (int q = 0; q < 4; ++q) *(f32x4*)(p + 4 * q) = x[q];
;             } else {
;                 u32x4 w0, w1, v0;
;                 w0.x = pk2(x[0][0], x[0][1]); w0.y = pk2(x[0][2], x[0][3]); w0.z = pk2(x[1][0], x[1][1]); w0.w = pk2(x[1][2], x[1][3]);
;                 w1.x = pk2(x[2][0], x[2][1]); w1.y = pk2(x[2][2], x[2][3]); w1.z = pk2(x[3][0], x[3][1]); w1.w = pk2(x[3][2], x[3][3]);
;                 v0.x = pk_lo8(x[0][0] - bflo(w0.x), x[0][1] - bfhi(w0.x), x[0][2] - bflo(w0.y), x[0][3] - bfhi(w0.y));
;                 v0.y = pk_lo8(x[1][0] - bflo(w0.z), x[1][1] - bfhi(w0.z), x[1][2] - bflo(w0.w), x[1][3] - bfhi(w0.w));
;                 v0.z = pk_lo8(x[2][0] - bflo(w1.x), x[2][1] - bfhi(w1.x), x[2][2] - bflo(w1.y), x[2][3] - bfhi(w1.y));
;                 v0.w = pk_lo8(x[3][0] - bflo(w1.z), x[3][1] - bfhi(w1.z), x[3][2] - bflo(w1.w), x[3][3] - bfhi(w1.w));
;                 u32x4* xb = (u32x4*)(XB + off); xb[0] = w0; xb[1] = w1;
;                 *(u32x4*)(XL + off) = v0;
;                 s += shx(s, LANE_, 16); s += shx(s, LANE_, 32);
;                 if (fq == 0) atomicAdd(ssq_next + row, s);
.LBB0_1064:
	s_nop 1
	v_add_co_u32_e32 v108, vcc, 0x48000, v206
	s_mov_b64 s[4:5], 0x48000
	s_nop 0
	v_addc_co_u32_e32 v109, vcc, 0, v207, vcc
	v_add_co_u32_e32 v116, vcc, 0x24000, v198
	v_lshl_add_u64 v[148:149], v[206:207], 0, s[4:5]
	s_nop 0
	v_addc_co_u32_e32 v117, vcc, 0, v199, vcc
	global_load_dwordx4 v[124:127], v[108:109], off nt
	s_nop 0
	global_load_dwordx4 v[108:111], v[148:149], off offset:16 nt
	v_cvt_f32_fp8_sdwa v220, v168 src0_sel:BYTE_2
	global_load_dwordx4 v[116:119], v[116:117], off nt
	v_cvt_f32_fp8_sdwa v221, v168 src0_sel:BYTE_3
	v_lshlrev_b32_e32 v150, 16, v172
	v_and_b32_e32 v151, 0xffff0000, v172
	v_cvt_f32_fp8_e32 v218, v168
	s_waitcnt lgkmcnt(0)
	v_cvt_f32_fp8_sdwa v219, v168 src0_sel:BYTE_1
	v_lshlrev_b32_e32 v172, 16, v173
	v_and_b32_e32 v173, 0xffff0000, v173
	v_pk_fma_f32 v[172:173], v[220:221], s[76:77], v[172:173] op_sel_hi:[1,0,1]
	v_cvt_f32_fp8_e32 v220, v169
	v_cvt_f32_fp8_sdwa v221, v169 src0_sel:BYTE_1
	v_cvt_f32_fp8_sdwa v168, v169 src0_sel:BYTE_2
	v_cvt_f32_fp8_sdwa v169, v169 src0_sel:BYTE_3
	v_cvt_f32_fp8_sdwa v222, v170 src0_sel:BYTE_2
	v_cvt_f32_fp8_sdwa v223, v170 src0_sel:BYTE_3
	v_pk_fma_f32 v[150:151], v[218:219], s[76:77], v[150:151] op_sel_hi:[1,0,1]
	v_lshlrev_b32_e32 v218, 16, v174
	v_and_b32_e32 v219, 0xffff0000, v174
	v_lshlrev_b32_e32 v174, 16, v175
	v_and_b32_e32 v175, 0xffff0000, v175
	v_pk_fma_f32 v[218:219], v[220:221], s[76:77], v[218:219] op_sel_hi:[1,0,1]
	v_pk_fma_f32 v[168:169], v[168:169], s[76:77], v[174:175] op_sel_hi:[1,0,1]
	v_lshlrev_b32_e32 v174, 16, v164
	v_and_b32_e32 v175, 0xffff0000, v164
	v_cvt_f32_fp8_e32 v220, v170
	v_cvt_f32_fp8_sdwa v221, v170 src0_sel:BYTE_1
	v_lshlrev_b32_e32 v164, 16, v165
	v_and_b32_e32 v165, 0xffff0000, v165
	v_pk_fma_f32 v[164:165], v[222:223], s[76:77], v[164:165] op_sel_hi:[1,0,1]
	v_cvt_f32_fp8_e32 v222, v171
	v_cvt_f32_fp8_sdwa v223, v171 src0_sel:BYTE_1
	v_cvt_f32_fp8_sdwa v170, v171 src0_sel:BYTE_2
	v_cvt_f32_fp8_sdwa v171, v171 src0_sel:BYTE_3
	v_readlane_b32 s22, v253, 36
	v_pk_fma_f32 v[174:175], v[220:221], s[76:77], v[174:175] op_sel_hi:[1,0,1]
	v_lshlrev_b32_e32 v220, 16, v166
	v_and_b32_e32 v221, 0xffff0000, v166
	v_lshlrev_b32_e32 v166, 16, v167
	v_and_b32_e32 v167, 0xffff0000, v167
	v_readlane_b32 s23, v253, 37
	v_pk_fma_f32 v[220:221], v[222:223], s[76:77], v[220:221] op_sel_hi:[1,0,1]
	v_pk_fma_f32 v[166:167], v[170:171], s[76:77], v[166:167] op_sel_hi:[1,0,1]
	v_pk_fma_f32 v[132:133], v[132:133], 0.5, v[150:151] op_sel_hi:[1,0,1]
	v_cndmask_b32_e64 v150, 0, 1, s[22:23]
	v_pk_fma_f32 v[134:135], v[134:135], 0.5, v[172:173] op_sel_hi:[1,0,1]
	v_pk_fma_f32 v[130:131], v[130:131], 0.5, v[168:169] op_sel_hi:[1,0,1]
	v_pk_fma_f32 v[128:129], v[128:129], 0.5, v[218:219] op_sel_hi:[1,0,1]
	v_pk_fma_f32 v[122:123], v[122:123], 0.5, v[164:165] op_sel_hi:[1,0,1]
	v_pk_fma_f32 v[120:121], v[120:121], 0.5, v[174:175] op_sel_hi:[1,0,1]
	v_pk_fma_f32 v[114:115], v[114:115], 0.5, v[166:167] op_sel_hi:[1,0,1]
	v_pk_fma_f32 v[112:113], v[112:113], 0.5, v[220:221] op_sel_hi:[1,0,1]
	v_cmp_ne_u32_e64 s[4:5], 1, v150
	s_andn2_b64 vcc, exec, s[22:23]
	s_mov_b64 s[22:23], -1
	s_cbranch_vccnz .LBB0_1068
	v_mul_f32_e32 v150, v133, v133
	v_mul_f32_e32 v151, v135, v135
	v_fmac_f32_e32 v150, v132, v132
	v_fmac_f32_e32 v151, v134, v134
	v_add_f32_e32 v150, v150, v151
	v_mul_f32_e32 v151, v129, v129
	v_mul_f32_e32 v164, v131, v131
	v_fmac_f32_e32 v151, v128, v128
	v_fmac_f32_e32 v164, v130, v130
	v_add_f32_e32 v151, v151, v164
	v_add_f32_e32 v150, v150, v151
	v_mul_f32_e32 v151, v121, v121
	v_mul_f32_e32 v164, v123, v123
	v_fmac_f32_e32 v151, v120, v120
	v_fmac_f32_e32 v164, v122, v122
	v_add_f32_e32 v151, v151, v164
	v_add_f32_e32 v150, v150, v151
	v_mul_f32_e32 v151, v113, v113
	v_mul_f32_e32 v164, v115, v115
	v_fmac_f32_e32 v151, v112, v112
	v_fmac_f32_e32 v164, v114, v114
	v_add_f32_e32 v151, v151, v164
	v_cvt_pk_bf16_f32 v164, v132, v133
	v_add_f32_e32 v150, v150, v151
	v_lshlrev_b32_e32 v151, 16, v164
	v_and_b32_e32 v172, 0xffff0000, v164
	v_sub_f32_e32 v151, v132, v151
	v_sub_f32_e32 v172, v133, v172
	v_mul_f32_e32 v151, 0x44000000, v151
	v_mul_f32_e32 v175, 0x44000000, v172
	v_mov_b32_e32 v172, v189
	v_cvt_pk_bf16_f32 v165, v134, v135
	v_cvt_pk_fp8_f32 v172, v151, v175
	v_lshlrev_b32_e32 v173, 16, v165
	v_and_b32_e32 v174, 0xffff0000, v165
	v_sub_f32_e32 v173, v134, v173
	v_sub_f32_e32 v151, v135, v174
	v_cvt_pk_bf16_f32 v166, v128, v129
	v_mul_f32_e32 v173, 0x44000000, v173
	v_mul_f32_e32 v151, 0x44000000, v151
	v_cvt_pk_fp8_f32 v172, v173, v151 op_sel:[0,0,1]
	v_lshlrev_b32_e32 v151, 16, v166
	v_and_b32_e32 v173, 0xffff0000, v166
	v_sub_f32_e32 v151, v128, v151
	v_sub_f32_e32 v173, v129, v173
	v_mul_f32_e32 v151, 0x44000000, v151
	v_mul_f32_e32 v218, 0x44000000, v173
	v_mov_b32_e32 v173, v189
	v_cvt_pk_bf16_f32 v167, v130, v131
	v_cvt_pk_fp8_f32 v173, v151, v218
	v_lshlrev_b32_e32 v174, 16, v167
	v_and_b32_e32 v175, 0xffff0000, v167
	v_sub_f32_e32 v174, v130, v174
	v_sub_f32_e32 v151, v131, v175
	v_cvt_pk_bf16_f32 v168, v120, v121
	v_mul_f32_e32 v174, 0x44000000, v174
	v_mul_f32_e32 v151, 0x44000000, v151
	v_cvt_pk_fp8_f32 v173, v174, v151 op_sel:[0,0,1]
	v_lshlrev_b32_e32 v151, 16, v168
	v_and_b32_e32 v174, 0xffff0000, v168
	v_sub_f32_e32 v151, v120, v151
	v_sub_f32_e32 v174, v121, v174
	v_mul_f32_e32 v151, 0x44000000, v151
	v_mul_f32_e32 v219, 0x44000000, v174
	v_mov_b32_e32 v174, v189
	v_cvt_pk_bf16_f32 v169, v122, v123
	v_cvt_pk_fp8_f32 v174, v151, v219
	v_lshlrev_b32_e32 v175, 16, v169
	v_and_b32_e32 v218, 0xffff0000, v169
	v_sub_f32_e32 v175, v122, v175
	v_sub_f32_e32 v151, v123, v218
	v_cvt_pk_bf16_f32 v170, v112, v113
	v_mul_f32_e32 v175, 0x44000000, v175
	v_mul_f32_e32 v151, 0x44000000, v151
	v_cvt_pk_fp8_f32 v174, v175, v151 op_sel:[0,0,1]
	v_lshlrev_b32_e32 v151, 16, v170
	v_and_b32_e32 v175, 0xffff0000, v170
	v_sub_f32_e32 v151, v112, v151
	v_sub_f32_e32 v175, v113, v175
	v_mul_f32_e32 v151, 0x44000000, v151
	v_mul_f32_e32 v220, 0x44000000, v175
	v_mov_b32_e32 v175, v189
	v_cvt_pk_fp8_f32 v175, v151, v220
	ds_bpermute_b32 v151, v214, v150
	v_cvt_pk_bf16_f32 v171, v114, v115
	v_lshlrev_b32_e32 v218, 16, v171
	v_and_b32_e32 v219, 0xffff0000, v171
	v_sub_f32_e32 v218, v114, v218
	s_waitcnt lgkmcnt(0)
	v_add_f32_e32 v150, v150, v151
	ds_bpermute_b32 v151, v215, v150
	v_sub_f32_e32 v219, v115, v219
	v_mul_f32_e32 v218, 0x44000000, v218
	v_mul_f32_e32 v219, 0x44000000, v219
	v_cvt_pk_fp8_f32 v175, v218, v219 op_sel:[0,0,1]
	s_mov_b64 s[22:23], 0x4000
	v_lshl_add_u64 v[218:219], v[198:199], 0, s[22:23]
	global_store_dwordx4 v[210:211], v[164:167], off
	global_store_dwordx4 v[210:211], v[168:171], off offset:16
	global_store_dwordx4 v[218:219], v[172:175], off
	s_and_saveexec_b64 s[22:23], s[0:1]
	s_cbranch_execz .LBB0_1067
	v_lshl_add_u64 v[164:165], v[186:187], 2, s[14:15]
	s_waitcnt lgkmcnt(0)
	v_add_f32_e32 v150, v150, v151
	global_atomic_add_f32 v[164:165], v150, off offset:64

; __device__ __forceinline__ float bflo(unsigned u) { return __uint_as_float(u << 16); }
; __device__ __forceinline__ float bfhi(unsigned u) { return __uint_as_float(u & 0xffff0000u); }
;     __device__ __forceinline__ void operator()(const AccT& acc, const Unit& u, int wr, int wc, int fr, int fq) const {
;     ...
;             if (idx + 4 < 8) { const size_t o = off0 + (size_t)(128 + (idx & 3) * 16) * DM;
;                 hr[idx & 3][0] = *(const u32x4*)(XB + o); hr[idx & 3][1] = *(const u32x4*)(XB + o + 8); lr[idx & 3] = *(const u32x4*)(XL + o); }
;             f32x4 x[4];
;             x[0] = (f32x4){bflo(h0.x), bfhi(h0.x), bflo(h0.y), bfhi(h0.y)} + un_lo8(l0.x);
;             x[1] = (f32x4){bflo(h0.z), bfhi(h0.z), bflo(h0.w), bfhi(h0.w)} + un_lo8(l0.y);
;             x[2] = (f32x4){bflo(h1.x), bfhi(h1.x), bflo(h1.y), bfhi(h1.y)} + un_lo8(l0.z);
;             x[3] = (f32x4){bflo(h1.z), bfhi(h1.z), bflo(h1.w), bfhi(h1.w)} + un_lo8(l0.w);
; #pragma unroll
;             for (int q = 0; q < 4; ++q) { x[q] = x[q] + scale * acc[ai][q >> 1][m][q & 1];
;                 s += (x[q][0] * x[q][0] + x[q][1] * x[q][1]) + (x[q][2] * x[q][2] + x[q][3] * x[q][3]); }
;             if (last) { float* p = OUT + off;
; #pragma unroll
;                 for (int q = 0; q < 4; ++q) *(f32x4*)(p + 4 * q) = x[q];
;             } else {
;                 u32x4 w0, w1, v0;
;                 w0.x = pk2(x[0][0], x[0][1]); w0.y = pk2(x[0][2], x[0][3]); w0.z = pk2(x[1][0], x[1][1]); w0.w = pk2(x[1][2], x[1][3]);
;                 w1.x = pk2(x[2][0], x[2][1]); w1.y = pk2(x[2][2], x[2][3]); w1.z = pk2(x[3][0], x[3][1]); w1.w = pk2(x[3][2], x[3][3]);
;                 v0.x = pk_lo8(x[0][0] - bflo(w0.x), x[0][1] - bfhi(w0.x), x[0][2] - bflo(w0.y), x[0][3] - bfhi(w0.y));
;                 v0.y = pk_lo8(x[1][0] - bflo(w0.z), x[1][1] - bfhi(w0.z), x[1][2] - bflo(w0.w), x[1][3] - bfhi(w0.w));
;                 v0.z = pk_lo8(x[2][0] - bflo(w1.x), x[2][1] - bfhi(w1.x), x[2][2] - bflo(w1.y), x[2][3] - bfhi(w1.y));
;                 v0.w = pk_lo8(x[3][0] - bflo(w1.z), x[3][1] - bfhi(w1.z), x[3][2] - bflo(w1.w), x[3][3] - bfhi(w1.w));
;                 u32x4* xb = (u32x4*)(XB + off); xb[0] = w0; xb[1] = w1;
;                 *(u32x4*)(XL + off) = v0;
;                 s += shx(s, LANE_, 16); s += shx(s, LANE_, 32);
;                 if (fq == 0) atomicAdd(ssq_next + row, s);
.LBB0_1070:
	s_nop 1
	v_add_co_u32_e32 v112, vcc, 0x50000, v206
	s_mov_b64 s[22:23], 0x50000
	s_nop 0
	v_addc_co_u32_e32 v113, vcc, 0, v207, vcc
	v_add_co_u32_e32 v120, vcc, 0x28000, v198
	v_lshl_add_u64 v[132:133], v[206:207], 0, s[22:23]
	s_nop 0
	v_addc_co_u32_e32 v121, vcc, 0, v199, vcc
	global_load_dwordx4 v[128:131], v[112:113], off nt
	s_nop 0
	global_load_dwordx4 v[112:115], v[132:133], off offset:16 nt
	v_cvt_f32_fp8_e32 v150, v156
	global_load_dwordx4 v[120:123], v[120:121], off nt
	s_waitcnt lgkmcnt(0)
	v_cvt_f32_fp8_sdwa v151, v156 src0_sel:BYTE_1
	v_cvt_f32_fp8_sdwa v164, v156 src0_sel:BYTE_2
	v_cvt_f32_fp8_sdwa v165, v156 src0_sel:BYTE_3
	v_lshlrev_b32_e32 v134, 16, v160
	v_and_b32_e32 v135, 0xffff0000, v160
	v_lshlrev_b32_e32 v160, 16, v161
	v_and_b32_e32 v161, 0xffff0000, v161
	v_pk_fma_f32 v[134:135], v[150:151], s[76:77], v[134:135] op_sel_hi:[1,0,1]
	v_pk_fma_f32 v[150:151], v[164:165], s[76:77], v[160:161] op_sel_hi:[1,0,1]
	v_cvt_f32_fp8_e32 v164, v157
	v_cvt_f32_fp8_sdwa v165, v157 src0_sel:BYTE_1
	v_cvt_f32_fp8_sdwa v156, v157 src0_sel:BYTE_2
	v_cvt_f32_fp8_sdwa v157, v157 src0_sel:BYTE_3
	v_cvt_f32_fp8_sdwa v166, v158 src0_sel:BYTE_2
	v_cvt_f32_fp8_sdwa v167, v158 src0_sel:BYTE_3
	v_lshlrev_b32_e32 v160, 16, v162
	v_and_b32_e32 v161, 0xffff0000, v162
	v_lshlrev_b32_e32 v162, 16, v163
	v_and_b32_e32 v163, 0xffff0000, v163
	v_pk_fma_f32 v[160:161], v[164:165], s[76:77], v[160:161] op_sel_hi:[1,0,1]
	v_pk_fma_f32 v[156:157], v[156:157], s[76:77], v[162:163] op_sel_hi:[1,0,1]
	v_lshlrev_b32_e32 v162, 16, v152
	v_and_b32_e32 v163, 0xffff0000, v152
	v_cvt_f32_fp8_e32 v164, v158
	v_cvt_f32_fp8_sdwa v165, v158 src0_sel:BYTE_1
	v_lshlrev_b32_e32 v152, 16, v153
	v_and_b32_e32 v153, 0xffff0000, v153
	v_pk_fma_f32 v[152:153], v[166:167], s[76:77], v[152:153] op_sel_hi:[1,0,1]
	v_cvt_f32_fp8_e32 v166, v159
	v_cvt_f32_fp8_sdwa v167, v159 src0_sel:BYTE_1
	v_cvt_f32_fp8_sdwa v158, v159 src0_sel:BYTE_2
	v_cvt_f32_fp8_sdwa v159, v159 src0_sel:BYTE_3
	v_pk_fma_f32 v[162:163], v[164:165], s[76:77], v[162:163] op_sel_hi:[1,0,1]
	v_lshlrev_b32_e32 v164, 16, v154
	v_and_b32_e32 v165, 0xffff0000, v154
	v_lshlrev_b32_e32 v154, 16, v155
	v_and_b32_e32 v155, 0xffff0000, v155
	v_pk_fma_f32 v[164:165], v[166:167], s[76:77], v[164:165] op_sel_hi:[1,0,1]
	v_pk_fma_f32 v[154:155], v[158:159], s[76:77], v[154:155] op_sel_hi:[1,0,1]
	v_pk_fma_f32 v[94:95], v[94:95], 0.5, v[150:151] op_sel_hi:[1,0,1]
	v_pk_fma_f32 v[92:93], v[92:93], 0.5, v[134:135] op_sel_hi:[1,0,1]
	v_pk_fma_f32 v[90:91], v[90:91], 0.5, v[156:157] op_sel_hi:[1,0,1]
	v_pk_fma_f32 v[88:89], v[88:89], 0.5, v[160:161] op_sel_hi:[1,0,1]
	v_pk_fma_f32 v[86:87], v[86:87], 0.5, v[152:153] op_sel_hi:[1,0,1]
	v_pk_fma_f32 v[84:85], v[84:85], 0.5, v[162:163] op_sel_hi:[1,0,1]
	v_pk_fma_f32 v[82:83], v[82:83], 0.5, v[154:155] op_sel_hi:[1,0,1]
	v_pk_fma_f32 v[80:81], v[80:81], 0.5, v[164:165] op_sel_hi:[1,0,1]
	s_and_b64 vcc, exec, s[4:5]
	s_mov_b64 s[22:23], -1
	s_cbranch_vccnz .LBB0_1074
	v_mul_f32_e32 v134, v93, v93
	v_mul_f32_e32 v135, v95, v95
	v_fmac_f32_e32 v134, v92, v92
	v_fmac_f32_e32 v135, v94, v94
	v_add_f32_e32 v134, v134, v135
	v_mul_f32_e32 v135, v89, v89
	v_mul_f32_e32 v150, v91, v91
	v_fmac_f32_e32 v135, v88, v88
	v_fmac_f32_e32 v150, v90, v90
	v_add_f32_e32 v135, v135, v150
	v_add_f32_e32 v134, v134, v135
	v_mul_f32_e32 v135, v85, v85
	v_mul_f32_e32 v150, v87, v87
	v_fmac_f32_e32 v135, v84, v84
	v_fmac_f32_e32 v150, v86, v86
	v_add_f32_e32 v135, v135, v150
	v_add_f32_e32 v134, v134, v135
	v_mul_f32_e32 v135, v81, v81
	v_mul_f32_e32 v150, v83, v83
	v_fmac_f32_e32 v135, v80, v80
	v_fmac_f32_e32 v150, v82, v82
	v_add_f32_e32 v135, v135, v150
	v_cvt_pk_bf16_f32 v150, v92, v93
	v_add_f32_e32 v134, v134, v135
	v_lshlrev_b32_e32 v135, 16, v150
	v_and_b32_e32 v158, 0xffff0000, v150
	v_sub_f32_e32 v135, v92, v135
	v_sub_f32_e32 v158, v93, v158
	v_mul_f32_e32 v135, 0x44000000, v135
	v_mul_f32_e32 v161, 0x44000000, v158
	v_mov_b32_e32 v158, v189
	v_cvt_pk_bf16_f32 v151, v94, v95
	v_cvt_pk_fp8_f32 v158, v135, v161
	v_lshlrev_b32_e32 v159, 16, v151
	v_and_b32_e32 v160, 0xffff0000, v151
	v_sub_f32_e32 v159, v94, v159
	v_sub_f32_e32 v135, v95, v160
	v_cvt_pk_bf16_f32 v152, v88, v89
	v_mul_f32_e32 v159, 0x44000000, v159
	v_mul_f32_e32 v135, 0x44000000, v135
	v_cvt_pk_fp8_f32 v158, v159, v135 op_sel:[0,0,1]
	v_lshlrev_b32_e32 v135, 16, v152
	v_and_b32_e32 v159, 0xffff0000, v152
	v_sub_f32_e32 v135, v88, v135
	v_sub_f32_e32 v159, v89, v159
	v_mul_f32_e32 v135, 0x44000000, v135
	v_mul_f32_e32 v162, 0x44000000, v159
	v_mov_b32_e32 v159, v189
	v_cvt_pk_bf16_f32 v153, v90, v91
	v_cvt_pk_fp8_f32 v159, v135, v162
	v_lshlrev_b32_e32 v160, 16, v153
	v_and_b32_e32 v161, 0xffff0000, v153
	v_sub_f32_e32 v160, v90, v160
	v_sub_f32_e32 v135, v91, v161
	v_cvt_pk_bf16_f32 v154, v84, v85
	v_mul_f32_e32 v160, 0x44000000, v160
	v_mul_f32_e32 v135, 0x44000000, v135
	v_cvt_pk_fp8_f32 v159, v160, v135 op_sel:[0,0,1]
	v_lshlrev_b32_e32 v135, 16, v154
	v_and_b32_e32 v160, 0xffff0000, v154
	v_sub_f32_e32 v135, v84, v135
	v_sub_f32_e32 v160, v85, v160
	v_mul_f32_e32 v135, 0x44000000, v135
	v_mul_f32_e32 v163, 0x44000000, v160
	v_mov_b32_e32 v160, v189
	v_cvt_pk_bf16_f32 v155, v86, v87
	v_cvt_pk_fp8_f32 v160, v135, v163
	v_lshlrev_b32_e32 v161, 16, v155
	v_and_b32_e32 v162, 0xffff0000, v155
	v_sub_f32_e32 v161, v86, v161
	v_sub_f32_e32 v135, v87, v162
	v_cvt_pk_bf16_f32 v156, v80, v81
	v_mul_f32_e32 v161, 0x44000000, v161
	v_mul_f32_e32 v135, 0x44000000, v135
	v_cvt_pk_fp8_f32 v160, v161, v135 op_sel:[0,0,1]
	v_lshlrev_b32_e32 v135, 16, v156
	v_and_b32_e32 v161, 0xffff0000, v156
	v_sub_f32_e32 v135, v80, v135
	v_sub_f32_e32 v161, v81, v161
	v_mul_f32_e32 v135, 0x44000000, v135
	v_mul_f32_e32 v164, 0x44000000, v161
	v_mov_b32_e32 v161, v189
	v_cvt_pk_fp8_f32 v161, v135, v164
	ds_bpermute_b32 v135, v214, v134
	v_cvt_pk_bf16_f32 v157, v82, v83
	v_lshlrev_b32_e32 v162, 16, v157
	v_and_b32_e32 v163, 0xffff0000, v157
	v_sub_f32_e32 v162, v82, v162
	s_waitcnt lgkmcnt(0)
	v_add_f32_e32 v134, v134, v135
	ds_bpermute_b32 v135, v215, v134
	v_sub_f32_e32 v163, v83, v163
	v_mul_f32_e32 v162, 0x44000000, v162
	v_mul_f32_e32 v163, 0x44000000, v163
	v_cvt_pk_fp8_f32 v161, v162, v163 op_sel:[0,0,1]
	s_mov_b64 s[22:23], 0x8000
	v_lshl_add_u64 v[162:163], v[198:199], 0, s[22:23]
	global_store_dwordx4 v[208:209], v[150:153], off
	global_store_dwordx4 v[208:209], v[154:157], off offset:16
	global_store_dwordx4 v[162:163], v[158:161], off
	s_and_saveexec_b64 s[22:23], s[0:1]
	s_cbranch_execz .LBB0_1073
	v_lshl_add_u64 v[150:151], v[186:187], 2, s[14:15]
	s_waitcnt lgkmcnt(0)
	v_add_f32_e32 v134, v134, v135
	global_atomic_add_f32 v[150:151], v134, off offset:128

;     __device__ __forceinline__ void operator()(const AccT& acc, const Unit& u, int wr, int wc, int fr, int fq) const {
;     ...
;         for (int idx = 0; idx < 8; ++idx) {
;             const int ai = idx >> 2, m = idx & 3, rofs = ai * 128 + m * 16;
;             const int row = row0 + rofs; float s = 0.f;
;             const size_t off = off0 + (size_t)rofs * DM;
;             const u32x4 h0 = hr[idx & 3][0], h1 = hr[idx & 3][1], l0 = lr[idx & 3];
;             if (idx + 4 < 8) { const size_t o = off0 + (size_t)(128 + (idx & 3) * 16) * DM;
;                 hr[idx & 3][0] = *(const u32x4*)(XB + o); hr[idx & 3][1] = *(const u32x4*)(XB + o + 8); lr[idx & 3] = *(const u32x4*)(XL + o); }
;             f32x4 x[4];
;             x[0] = (f32x4){bflo(h0.x), bfhi(h0.x), bflo(h0.y), bfhi(h0.y)} + un_lo8(l0.x);
;             x[1] = (f32x4){bflo(h0.z), bfhi(h0.z), bflo(h0.w), bfhi(h0.w)} + un_lo8(l0.y);
;             x[2] = (f32x4){bflo(h1.x), bfhi(h1.x), bflo(h1.y), bfhi(h1.y)} + un_lo8(l0.z);
;             x[3] = (f32x4){bflo(h1.z), bfhi(h1.z), bflo(h1.w), bfhi(h1.w)} + un_lo8(l0.w);
; #pragma unroll
;             for (int q = 0; q < 4; ++q) { x[q] = x[q] + scale * acc[ai][q >> 1][m][q & 1];
;                 s += (x[q][0] * x[q][0] + x[q][1] * x[q][1]) + (x[q][2] * x[q][2] + x[q][3] * x[q][3]); }
;             if (last) { float* p = OUT + off;
; #pragma unroll
;                 for (int q = 0; q < 4; ++q) *(f32x4*)(p + 4 * q) = x[q];
;             } else {
;                 u32x4 w0, w1, v0;
;                 w0.x = pk2(x[0][0], x[0][1]); w0.y = pk2(x[0][2], x[0][3]); w0.z = pk2(x[1][0], x[1][1]); w0.w = pk2(x[1][2], x[1][3]);
;                 w1.x = pk2(x[2][0], x[2][1]); w1.y = pk2(x[2][2], x[2][3]); w1.z = pk2(x[3][0], x[3][1]); w1.w = pk2(x[3][2], x[3][3]);
;                 v0.x = pk_lo8(x[0][0] - bflo(w0.x), x[0][1] - bfhi(w0.x), x[0][2] - bflo(w0.y), x[0][3] - bfhi(w0.y));
;                 v0.y = pk_lo8(x[1][0] - bflo(w0.z), x[1][1] - bfhi(w0.z), x[1][2] - bflo(w0.w), x[1][3] - bfhi(w0.w));
;                 v0.z = pk_lo8(x[2][0] - bflo(w1.x), x[2][1] - bfhi(w1.x), x[2][2] - bflo(w1.y), x[2][3] - bfhi(w1.y));
;                 v0.w = pk_lo8(x[3][0] - bflo(w1.z), x[3][1] - bfhi(w1.z), x[3][2] - bflo(w1.w), x[3][3] - bfhi(w1.w));
;                 u32x4* xb = (u32x4*)(XB + off); xb[0] = w0; xb[1] = w1;
;                 *(u32x4*)(XL + off) = v0;
.LBB0_1076:
	s_nop 1
	v_add_co_u32_e32 v80, vcc, 0x58000, v206
	v_lshl_add_u64 v[92:93], v[206:207], 0, s[90:91]
	s_nop 0
	v_addc_co_u32_e32 v81, vcc, 0, v207, vcc
	v_add_co_u32_e32 v84, vcc, 0x2c000, v198
	global_load_dwordx4 v[88:91], v[80:81], off nt
	s_nop 0
	global_load_dwordx4 v[80:83], v[92:93], off offset:16 nt
	v_addc_co_u32_e32 v85, vcc, 0, v199, vcc
	global_load_dwordx4 v[84:87], v[84:85], off nt
	v_cvt_f32_fp8_e32 v134, v140
	s_waitcnt lgkmcnt(0)
	v_cvt_f32_fp8_sdwa v135, v140 src0_sel:BYTE_1
	v_cvt_f32_fp8_sdwa v150, v140 src0_sel:BYTE_2
	v_cvt_f32_fp8_sdwa v151, v140 src0_sel:BYTE_3
	v_lshlrev_b32_e32 v94, 16, v144
	v_and_b32_e32 v95, 0xffff0000, v144
	v_lshlrev_b32_e32 v144, 16, v145
	v_and_b32_e32 v145, 0xffff0000, v145
	v_pk_fma_f32 v[94:95], v[134:135], s[76:77], v[94:95] op_sel_hi:[1,0,1]
	v_pk_fma_f32 v[134:135], v[150:151], s[76:77], v[144:145] op_sel_hi:[1,0,1]
	v_cvt_f32_fp8_e32 v150, v141
	v_cvt_f32_fp8_sdwa v151, v141 src0_sel:BYTE_1
	v_cvt_f32_fp8_sdwa v140, v141 src0_sel:BYTE_2
	v_cvt_f32_fp8_sdwa v141, v141 src0_sel:BYTE_3
	v_cvt_f32_fp8_sdwa v152, v142 src0_sel:BYTE_2
	v_cvt_f32_fp8_sdwa v153, v142 src0_sel:BYTE_3
	v_lshlrev_b32_e32 v144, 16, v146
	v_and_b32_e32 v145, 0xffff0000, v146
	v_lshlrev_b32_e32 v146, 16, v147
	v_and_b32_e32 v147, 0xffff0000, v147
	v_pk_fma_f32 v[144:145], v[150:151], s[76:77], v[144:145] op_sel_hi:[1,0,1]
	v_pk_fma_f32 v[140:141], v[140:141], s[76:77], v[146:147] op_sel_hi:[1,0,1]
	v_lshlrev_b32_e32 v146, 16, v136
	v_and_b32_e32 v147, 0xffff0000, v136
	v_cvt_f32_fp8_e32 v150, v142
	v_cvt_f32_fp8_sdwa v151, v142 src0_sel:BYTE_1
	v_lshlrev_b32_e32 v136, 16, v137
	v_and_b32_e32 v137, 0xffff0000, v137
	v_pk_fma_f32 v[136:137], v[152:153], s[76:77], v[136:137] op_sel_hi:[1,0,1]
	v_cvt_f32_fp8_e32 v152, v143
	v_cvt_f32_fp8_sdwa v153, v143 src0_sel:BYTE_1
	v_cvt_f32_fp8_sdwa v142, v143 src0_sel:BYTE_2
	v_cvt_f32_fp8_sdwa v143, v143 src0_sel:BYTE_3
	v_pk_fma_f32 v[146:147], v[150:151], s[76:77], v[146:147] op_sel_hi:[1,0,1]
	v_lshlrev_b32_e32 v150, 16, v138
	v_and_b32_e32 v151, 0xffff0000, v138
	v_lshlrev_b32_e32 v138, 16, v139
	v_and_b32_e32 v139, 0xffff0000, v139
	v_pk_fma_f32 v[150:151], v[152:153], s[76:77], v[150:151] op_sel_hi:[1,0,1]
	v_pk_fma_f32 v[138:139], v[142:143], s[76:77], v[138:139] op_sel_hi:[1,0,1]
	v_pk_fma_f32 v[78:79], v[78:79], 0.5, v[134:135] op_sel_hi:[1,0,1]
	v_pk_fma_f32 v[76:77], v[76:77], 0.5, v[94:95] op_sel_hi:[1,0,1]
	v_pk_fma_f32 v[74:75], v[74:75], 0.5, v[140:141] op_sel_hi:[1,0,1]
	v_pk_fma_f32 v[72:73], v[72:73], 0.5, v[144:145] op_sel_hi:[1,0,1]
	v_pk_fma_f32 v[70:71], v[70:71], 0.5, v[136:137] op_sel_hi:[1,0,1]
	v_pk_fma_f32 v[68:69], v[68:69], 0.5, v[146:147] op_sel_hi:[1,0,1]
	v_pk_fma_f32 v[66:67], v[66:67], 0.5, v[138:139] op_sel_hi:[1,0,1]
	v_pk_fma_f32 v[64:65], v[64:65], 0.5, v[150:151] op_sel_hi:[1,0,1]
	s_and_b64 vcc, exec, s[4:5]
	s_mov_b64 s[22:23], -1
	s_cbranch_vccnz .LBB0_1080
	v_mul_f32_e32 v94, v77, v77
	v_mul_f32_e32 v95, v79, v79
	v_fmac_f32_e32 v94, v76, v76
	v_fmac_f32_e32 v95, v78, v78
	v_add_f32_e32 v94, v94, v95
	v_mul_f32_e32 v95, v73, v73
	v_mul_f32_e32 v134, v75, v75
	v_fmac_f32_e32 v95, v72, v72
	v_fmac_f32_e32 v134, v74, v74
	v_add_f32_e32 v95, v95, v134
	v_add_f32_e32 v94, v94, v95
	v_mul_f32_e32 v95, v69, v69
	v_mul_f32_e32 v134, v71, v71
	v_fmac_f32_e32 v95, v68, v68
	v_fmac_f32_e32 v134, v70, v70
	v_add_f32_e32 v95, v95, v134
	v_add_f32_e32 v94, v94, v95
	v_mul_f32_e32 v95, v65, v65
	v_mul_f32_e32 v134, v67, v67
	v_fmac_f32_e32 v95, v64, v64
	v_fmac_f32_e32 v134, v66, v66
	v_add_f32_e32 v95, v95, v134
	v_cvt_pk_bf16_f32 v134, v76, v77
	v_add_f32_e32 v94, v94, v95
	v_lshlrev_b32_e32 v95, 16, v134
	v_and_b32_e32 v142, 0xffff0000, v134
	v_sub_f32_e32 v95, v76, v95
	v_sub_f32_e32 v142, v77, v142
	v_mul_f32_e32 v95, 0x44000000, v95
	v_mul_f32_e32 v145, 0x44000000, v142
	v_mov_b32_e32 v142, v189
	v_cvt_pk_bf16_f32 v135, v78, v79
	v_cvt_pk_fp8_f32 v142, v95, v145
	v_lshlrev_b32_e32 v143, 16, v135
	v_and_b32_e32 v144, 0xffff0000, v135
	v_sub_f32_e32 v143, v78, v143
	v_sub_f32_e32 v95, v79, v144
	v_cvt_pk_bf16_f32 v136, v72, v73
	v_mul_f32_e32 v143, 0x44000000, v143
	v_mul_f32_e32 v95, 0x44000000, v95
	v_cvt_pk_fp8_f32 v142, v143, v95 op_sel:[0,0,1]
	v_lshlrev_b32_e32 v95, 16, v136
	v_and_b32_e32 v143, 0xffff0000, v136
	v_sub_f32_e32 v95, v72, v95
	v_sub_f32_e32 v143, v73, v143
	v_mul_f32_e32 v95, 0x44000000, v95
	v_mul_f32_e32 v146, 0x44000000, v143
	v_mov_b32_e32 v143, v189
	v_cvt_pk_bf16_f32 v137, v74, v75
	v_cvt_pk_fp8_f32 v143, v95, v146
	v_lshlrev_b32_e32 v144, 16, v137
	v_and_b32_e32 v145, 0xffff0000, v137
	v_sub_f32_e32 v144, v74, v144
	v_sub_f32_e32 v95, v75, v145
	v_cvt_pk_bf16_f32 v138, v68, v69
	v_mul_f32_e32 v144, 0x44000000, v144
	v_mul_f32_e32 v95, 0x44000000, v95
	v_cvt_pk_fp8_f32 v143, v144, v95 op_sel:[0,0,1]
	v_lshlrev_b32_e32 v95, 16, v138
	v_and_b32_e32 v144, 0xffff0000, v138
	v_sub_f32_e32 v95, v68, v95
	v_sub_f32_e32 v144, v69, v144
	v_mul_f32_e32 v95, 0x44000000, v95
	v_mul_f32_e32 v147, 0x44000000, v144
	v_mov_b32_e32 v144, v189
	v_cvt_pk_bf16_f32 v139, v70, v71
	v_cvt_pk_fp8_f32 v144, v95, v147
	v_lshlrev_b32_e32 v145, 16, v139
	v_and_b32_e32 v146, 0xffff0000, v139
	v_sub_f32_e32 v145, v70, v145
	v_sub_f32_e32 v95, v71, v146
	v_cvt_pk_bf16_f32 v140, v64, v65
	v_mul_f32_e32 v145, 0x44000000, v145
	v_mul_f32_e32 v95, 0x44000000, v95
	v_cvt_pk_fp8_f32 v144, v145, v95 op_sel:[0,0,1]
	v_lshlrev_b32_e32 v95, 16, v140
	v_and_b32_e32 v145, 0xffff0000, v140
	v_sub_f32_e32 v95, v64, v95
	v_sub_f32_e32 v145, v65, v145
	v_mul_f32_e32 v95, 0x44000000, v95
	v_mul_f32_e32 v150, 0x44000000, v145
	v_mov_b32_e32 v145, v189
	v_cvt_pk_fp8_f32 v145, v95, v150
	ds_bpermute_b32 v95, v214, v94
	v_cvt_pk_bf16_f32 v141, v66, v67
	v_lshlrev_b32_e32 v146, 16, v141
	v_and_b32_e32 v147, 0xffff0000, v141
	v_sub_f32_e32 v146, v66, v146
	s_waitcnt lgkmcnt(0)
	v_add_f32_e32 v94, v94, v95
	ds_bpermute_b32 v95, v215, v94
	v_sub_f32_e32 v147, v67, v147
	v_mul_f32_e32 v146, 0x44000000, v146
	v_mul_f32_e32 v147, 0x44000000, v147
	v_cvt_pk_fp8_f32 v145, v146, v147 op_sel:[0,0,1]
	s_mov_b64 s[22:23], 0xc000
	v_lshl_add_u64 v[146:147], v[198:199], 0, s[22:23]
	global_store_dwordx4 v[204:205], v[134:137], off
	global_store_dwordx4 v[204:205], v[138:141], off offset:16
	global_store_dwordx4 v[146:147], v[142:145], off
	s_and_saveexec_b64 s[22:23], s[0:1]
	s_cbranch_execz .LBB0_1079
	v_lshl_add_u64 v[134:135], v[186:187], 2, s[14:15]
	s_waitcnt lgkmcnt(0)
	v_add_f32_e32 v94, v94, v95
	global_atomic_add_f32 v[134:135], v94, off offset:192
